# attention item epilogue: merge LDS reads software-pipelined (alternating destination pairs), next-item atomic wait deferred to slot publish
# baseline (speedup 1.0000x reference)
; __device__ __forceinline__ float fast_exp2(float x) { return __builtin_amdgcn_exp2f(x); }
; template <int DQ, int TYPE>
; __device__ __forceinline__ void attn_item(PP p, int layer, int b, int h, int qt, char* lds, const int tid_, unsigned* next_ctr, volatile XLAS unsigned* slot) {
;     ...
;     __builtin_amdgcn_s_setprio(0);
;     unsigned nxt_item = 0; if (tid_ == 0) nxt_item = atomicAdd(next_ctr, 1u);
;     l_run += __shfl_xor(l_run, 32);
;     float* mrg = (float*)lds;
;     {
;         float* mp = mrg + (size_t)((qg * 2 + kh) * 34) * 64 + lane;
;         if (kh == 0) {
; #pragma unroll
;             for (int t2 = 0; t2 < 2; ++t2)
; #pragma unroll
;                 for (int i = 0; i < 16; ++i) mp[(t2 * 16 + i) * 64] = O[2 + t2][i];
;         } else {
; #pragma unroll
;             for (int t2 = 0; t2 < 2; ++t2)
; #pragma unroll
;                 for (int i = 0; i < 16; ++i) mp[(t2 * 16 + i) * 64] = O[t2][i];
;         }
;         mp[32 * 64] = m_run; mp[33 * 64] = l_run;
;     }
;     __syncthreads();
;     {
;         const float* mp = mrg + (size_t)((qg * 2 + (kh ^ 1)) * 34) * 64 + lane;
;         const float m1 = mp[32 * 64], l1 = mp[33 * 64];
;         const float mt = fmaxf(m_run, m1);
;         const float a0 = fast_exp2(m_run - mt), a1 = fast_exp2(m1 - mt);
;         const float inv = 1.0f / (l_run * a0 + l1 * a1);
.LBB0_418:
	s_or_b64 exec, exec, s[12:13]
	s_load_dwordx2 s[14:15], s[0:1], 0x98
	s_lshl_b32 s12, s55, 12
	v_and_b32_e32 v2, 64, v224
	v_xor_b32_e32 v0, 32, v224
	v_add_u32_e32 v2, 64, v2
	s_waitcnt lgkmcnt(0)
	s_add_u32 s12, s14, s12
	s_addc_u32 s13, s15, 0
	s_lshl_b32 s14, s57, 1
	s_add_u32 s12, s12, s14
	v_cmp_lt_i32_e32 vcc, v0, v2
	s_addc_u32 s13, s13, 0
	s_lshl_b32 s14, s49, 1
	v_cndmask_b32_e32 v0, v224, v0, vcc
	s_add_i32 s15, s14, s56
	v_lshlrev_b32_e32 v0, 2, v0
	s_mulk_i32 s15, 0x2200
	ds_bpermute_b32 v0, v0, v158
	s_add_i32 s15, s15, 16
	v_lshlrev_b32_e32 v2, 2, v156
	v_add_u32_e32 v3, s15, v2
	s_xor_b32 s15, s56, 1
	s_add_i32 s14, s14, s15
	s_mulk_i32 s14, 0x2200
	v_cndmask_b32_e64 v12, v40, v72, s[52:53]
	v_cndmask_b32_e64 v83, v33, v65, s[52:53]
	v_cndmask_b32_e64 v84, v32, v64, s[52:53]
	s_add_i32 s14, s14, 16
	s_waitcnt lgkmcnt(0)
	v_add_f32_e32 v0, v158, v0
	v_cndmask_b32_e64 v4, v47, v79, s[52:53]
	v_cndmask_b32_e64 v5, v46, v78, s[52:53]
	v_cndmask_b32_e64 v6, v45, v77, s[52:53]
	v_cndmask_b32_e64 v7, v44, v76, s[52:53]
	v_cndmask_b32_e64 v8, v43, v75, s[52:53]
	v_cndmask_b32_e64 v9, v42, v74, s[52:53]
	v_cndmask_b32_e64 v11, v41, v73, s[52:53]
	v_cndmask_b32_e64 v13, v39, v71, s[52:53]
	v_cndmask_b32_e64 v14, v38, v70, s[52:53]
	v_cndmask_b32_e64 v15, v37, v69, s[52:53]
	v_cndmask_b32_e64 v80, v36, v68, s[52:53]
	v_cndmask_b32_e64 v81, v35, v67, s[52:53]
	v_cndmask_b32_e64 v82, v34, v66, s[52:53]
	v_cndmask_b32_e64 v85, v31, v63, s[52:53]
	v_cndmask_b32_e64 v86, v30, v62, s[52:53]
	v_cndmask_b32_e64 v87, v29, v61, s[52:53]
	v_cndmask_b32_e64 v88, v28, v60, s[52:53]
	v_cndmask_b32_e64 v89, v27, v59, s[52:53]
	v_cndmask_b32_e64 v90, v26, v58, s[52:53]
	v_cndmask_b32_e64 v91, v25, v57, s[52:53]
	v_cndmask_b32_e64 v92, v24, v56, s[52:53]
	v_cndmask_b32_e64 v93, v23, v55, s[52:53]
	v_cndmask_b32_e64 v94, v22, v54, s[52:53]
	v_cndmask_b32_e64 v95, v21, v53, s[52:53]
	s_waitcnt vmcnt(3)
	v_cndmask_b32_e64 v96, v20, v52, s[52:53]
	v_cndmask_b32_e64 v97, v19, v51, s[52:53]
	v_cndmask_b32_e64 v98, v18, v50, s[52:53]
	v_cndmask_b32_e64 v99, v17, v49, s[52:53]
	s_waitcnt vmcnt(2)
	v_cndmask_b32_e64 v100, v16, v48, s[52:53]
	ds_write2st64_b32 v3, v84, v83 offset1:1
	ds_write2st64_b32 v3, v82, v81 offset0:2 offset1:3
	ds_write2st64_b32 v3, v80, v15 offset0:4 offset1:5
	ds_write2st64_b32 v3, v14, v13 offset0:6 offset1:7
	ds_write2st64_b32 v3, v12, v11 offset0:8 offset1:9
	ds_write2st64_b32 v3, v9, v8 offset0:10 offset1:11
	ds_write2st64_b32 v3, v7, v6 offset0:12 offset1:13
	ds_write2st64_b32 v3, v5, v4 offset0:14 offset1:15
	ds_write2st64_b32 v3, v100, v99 offset0:16 offset1:17
	ds_write2st64_b32 v3, v98, v97 offset0:18 offset1:19
	ds_write2st64_b32 v3, v96, v95 offset0:20 offset1:21
	ds_write2st64_b32 v3, v94, v93 offset0:22 offset1:23
	ds_write2st64_b32 v3, v92, v91 offset0:24 offset1:25
	ds_write2st64_b32 v3, v90, v89 offset0:26 offset1:27
	ds_write2st64_b32 v3, v88, v87 offset0:28 offset1:29
	ds_write2st64_b32 v3, v86, v85 offset0:30 offset1:31
	ds_write2st64_b32 v3, v168, v0 offset0:32 offset1:33
	v_add_u32_e32 v12, s14, v2
	s_waitcnt lgkmcnt(0)
	s_barrier
	ds_read2st64_b32 v[4:5], v12 offset0:32 offset1:33
	v_max_f32_e32 v3, v168, v168
	s_waitcnt lgkmcnt(0)
	v_max_f32_e32 v2, v4, v4
	v_max_f32_e32 v2, v3, v2
	v_sub_f32_e32 v6, v168, v2
	v_sub_f32_e32 v2, v4, v2
	v_exp_f32_e32 v3, v2
	v_exp_f32_e32 v4, v6
	v_mul_f32_e32 v2, v5, v3
	v_fmac_f32_e32 v2, v0, v4
	v_div_scale_f32 v0, s[14:15], v2, v2, 1.0
	v_rcp_f32_e32 v5, v0
	s_nop 0
	v_fma_f32 v6, -v0, v5, 1.0
	v_fmac_f32_e32 v5, v6, v5
	v_div_scale_f32 v6, vcc, 1.0, v2, 1.0
	v_mul_f32_e32 v7, v6, v5
	v_fma_f32 v8, -v0, v7, v6
	v_fmac_f32_e32 v7, v8, v5
	v_fma_f32 v0, -v0, v7, v6
	v_div_fmas_f32 v0, v0, v5, v7
	v_div_fixup_f32 v11, v0, v2, 1.0
	v_lshlrev_b32_e32 v0, 12, v154
	v_lshl_add_u64 v[6:7], s[12:13], 0, v[0:1]
	s_mov_b64 s[12:13], 0x27388800
	v_lshl_add_u64 v[6:7], v[6:7], 0, s[12:13]
	s_mov_b64 s[12:13], -1
	s_andn2_b64 vcc, exec, s[8:9]
	v_lshlrev_b32_e32 v0, 1, v155
	s_cbranch_vccnz .LBB0_680
; template <int DQ, int TYPE>
; __device__ __forceinline__ void attn_item(PP p, int layer, int b, int h, int qt, char* lds, const int tid_, unsigned* next_ctr, volatile XLAS unsigned* slot) {
;     ...
;         bf16_t* orow = Op + (size_t)qpos * D;
;     ...
;         if (kh == 0) A_MERGE(0); else A_MERGE(2);
	ds_read2st64_b32 v[14:15], v12 offset1:1
	v_mov_b32_e32 v2, v64
	v_lshl_add_u64 v[8:9], v[6:7], 0, v[0:1]
	s_waitcnt lgkmcnt(0)
	ds_read2st64_b32 v[246:247], v12 offset0:2 offset1:3
	v_mov_b32_e32 v5, v14
	v_pk_mul_f32 v[80:81], v[2:3], v[4:5]
	v_mov_b32_e32 v5, v15
	v_add_f32_e32 v2, v80, v81
	v_mul_f32_e32 v13, v11, v2
	v_mov_b32_e32 v2, v65
	v_pk_mul_f32 v[14:15], v[2:3], v[4:5]
	s_nop 0
	v_add_f32_e32 v2, v14, v15
	v_mul_f32_e32 v80, v11, v2
	v_mov_b32_e32 v2, v66
	s_waitcnt lgkmcnt(0)
	ds_read2st64_b32 v[14:15], v12 offset0:4 offset1:5
	v_mov_b32_e32 v5, v246
	v_pk_mul_f32 v[64:65], v[2:3], v[4:5]
	v_mov_b32_e32 v5, v247
	v_add_f32_e32 v2, v64, v65
	v_mul_f32_e32 v64, v11, v2
	v_mov_b32_e32 v2, v67
	v_pk_mul_f32 v[246:247], v[2:3], v[4:5]
	s_nop 0
	v_add_f32_e32 v2, v246, v247
	v_mul_f32_e32 v2, v11, v2
	v_cvt_pk_bf16_f32 v246, v13, v80
	v_cvt_pk_bf16_f32 v247, v64, v2
	global_store_dwordx2 v[8:9], v[246:247], off offset:128
	v_mov_b32_e32 v2, v68
	s_waitcnt lgkmcnt(0)
	ds_read2st64_b32 v[246:247], v12 offset0:6 offset1:7
	v_mov_b32_e32 v5, v14
	v_pk_mul_f32 v[64:65], v[2:3], v[4:5]
	v_mov_b32_e32 v5, v15
	v_add_f32_e32 v2, v64, v65
	v_mul_f32_e32 v13, v11, v2
	v_mov_b32_e32 v2, v69
	v_pk_mul_f32 v[14:15], v[2:3], v[4:5]
	s_nop 0
	v_add_f32_e32 v2, v14, v15
	v_mul_f32_e32 v66, v11, v2
	v_mov_b32_e32 v2, v70
	s_waitcnt lgkmcnt(0)
	ds_read2st64_b32 v[14:15], v12 offset0:8 offset1:9
	v_mov_b32_e32 v5, v246
	v_pk_mul_f32 v[64:65], v[2:3], v[4:5]
	v_mov_b32_e32 v5, v247
	v_add_f32_e32 v2, v64, v65
	v_mul_f32_e32 v64, v11, v2
	v_mov_b32_e32 v2, v71
	v_pk_mul_f32 v[246:247], v[2:3], v[4:5]
	s_nop 0
	v_add_f32_e32 v2, v246, v247
	v_mul_f32_e32 v2, v11, v2
	v_cvt_pk_bf16_f32 v246, v13, v66
	v_cvt_pk_bf16_f32 v247, v64, v2
	global_store_dwordx2 v[8:9], v[246:247], off offset:144
	v_mov_b32_e32 v2, v72
	s_waitcnt lgkmcnt(0)
	ds_read2st64_b32 v[246:247], v12 offset0:10 offset1:11
	v_mov_b32_e32 v5, v14
	v_pk_mul_f32 v[64:65], v[2:3], v[4:5]
	v_mov_b32_e32 v5, v15
	v_add_f32_e32 v2, v64, v65
	v_mul_f32_e32 v13, v11, v2
	v_mov_b32_e32 v2, v73
	v_pk_mul_f32 v[14:15], v[2:3], v[4:5]
	s_nop 0
	v_add_f32_e32 v2, v14, v15
	v_mul_f32_e32 v66, v11, v2
	v_mov_b32_e32 v2, v74
	s_waitcnt lgkmcnt(0)
	ds_read2st64_b32 v[14:15], v12 offset0:12 offset1:13
	v_mov_b32_e32 v5, v246
	v_pk_mul_f32 v[64:65], v[2:3], v[4:5]
	v_mov_b32_e32 v5, v247
	v_add_f32_e32 v2, v64, v65
	v_mul_f32_e32 v64, v11, v2
	v_mov_b32_e32 v2, v75
	v_pk_mul_f32 v[246:247], v[2:3], v[4:5]
	s_nop 0
	v_add_f32_e32 v2, v246, v247
	v_mul_f32_e32 v2, v11, v2
	v_cvt_pk_bf16_f32 v246, v13, v66
	v_cvt_pk_bf16_f32 v247, v64, v2
	global_store_dwordx2 v[8:9], v[246:247], off offset:160
	v_mov_b32_e32 v2, v76
	s_waitcnt lgkmcnt(0)
	ds_read2st64_b32 v[246:247], v12 offset0:14 offset1:15
	v_mov_b32_e32 v5, v14
	v_pk_mul_f32 v[64:65], v[2:3], v[4:5]
	v_mov_b32_e32 v5, v15
	v_add_f32_e32 v2, v64, v65
	v_mul_f32_e32 v13, v11, v2
	v_mov_b32_e32 v2, v77
	v_pk_mul_f32 v[14:15], v[2:3], v[4:5]
	s_nop 0
	v_add_f32_e32 v2, v14, v15
	v_mul_f32_e32 v66, v11, v2
	v_mov_b32_e32 v2, v78
	s_waitcnt lgkmcnt(0)
	ds_read2st64_b32 v[14:15], v12 offset0:16 offset1:17
	v_mov_b32_e32 v5, v246
	v_pk_mul_f32 v[64:65], v[2:3], v[4:5]
	v_mov_b32_e32 v5, v247
	v_add_f32_e32 v2, v64, v65
	v_mul_f32_e32 v64, v11, v2
	v_mov_b32_e32 v2, v79
	v_pk_mul_f32 v[246:247], v[2:3], v[4:5]
	s_nop 0
	v_add_f32_e32 v2, v246, v247
	v_mul_f32_e32 v2, v11, v2
	v_cvt_pk_bf16_f32 v246, v13, v66
	v_cvt_pk_bf16_f32 v247, v64, v2
	global_store_dwordx2 v[8:9], v[246:247], off offset:176
	v_mov_b32_e32 v2, v48
	s_waitcnt lgkmcnt(0)
	ds_read2st64_b32 v[246:247], v12 offset0:18 offset1:19
	v_mov_b32_e32 v5, v14
	v_pk_mul_f32 v[64:65], v[2:3], v[4:5]
	v_mov_b32_e32 v5, v15
	v_add_f32_e32 v2, v64, v65
	v_mul_f32_e32 v13, v11, v2
	v_mov_b32_e32 v2, v49
	v_pk_mul_f32 v[14:15], v[2:3], v[4:5]
	s_nop 0
	v_add_f32_e32 v2, v14, v15
	v_mul_f32_e32 v64, v11, v2
	v_mov_b32_e32 v2, v50
	s_waitcnt lgkmcnt(0)
	ds_read2st64_b32 v[14:15], v12 offset0:20 offset1:21
	v_mov_b32_e32 v5, v246
	v_pk_mul_f32 v[48:49], v[2:3], v[4:5]
	v_mov_b32_e32 v5, v247
	v_add_f32_e32 v2, v48, v49
	v_mul_f32_e32 v48, v11, v2
	v_mov_b32_e32 v2, v51
	v_pk_mul_f32 v[246:247], v[2:3], v[4:5]
	s_nop 0
	v_add_f32_e32 v2, v246, v247
	v_mul_f32_e32 v2, v11, v2
	v_cvt_pk_bf16_f32 v246, v13, v64
	v_cvt_pk_bf16_f32 v247, v48, v2
	global_store_dwordx2 v[8:9], v[246:247], off offset:192
	v_mov_b32_e32 v2, v52
	s_waitcnt lgkmcnt(0)
	ds_read2st64_b32 v[246:247], v12 offset0:22 offset1:23
	v_mov_b32_e32 v5, v14
	v_pk_mul_f32 v[48:49], v[2:3], v[4:5]
	v_mov_b32_e32 v5, v15
	v_add_f32_e32 v2, v48, v49
	v_mul_f32_e32 v13, v11, v2
	v_mov_b32_e32 v2, v53
	v_pk_mul_f32 v[14:15], v[2:3], v[4:5]
	s_nop 0
	v_add_f32_e32 v2, v14, v15
	v_mul_f32_e32 v50, v11, v2
	v_mov_b32_e32 v2, v54
	s_waitcnt lgkmcnt(0)
	ds_read2st64_b32 v[14:15], v12 offset0:24 offset1:25
	v_mov_b32_e32 v5, v246
	v_pk_mul_f32 v[48:49], v[2:3], v[4:5]
	v_mov_b32_e32 v5, v247
	v_add_f32_e32 v2, v48, v49
	v_mul_f32_e32 v48, v11, v2
	v_mov_b32_e32 v2, v55
	v_pk_mul_f32 v[246:247], v[2:3], v[4:5]
	s_nop 0
	v_add_f32_e32 v2, v246, v247
	v_mul_f32_e32 v2, v11, v2
	v_cvt_pk_bf16_f32 v246, v13, v50
	v_cvt_pk_bf16_f32 v247, v48, v2
	global_store_dwordx2 v[8:9], v[246:247], off offset:208
	v_mov_b32_e32 v2, v56
	s_waitcnt lgkmcnt(0)
	ds_read2st64_b32 v[246:247], v12 offset0:26 offset1:27
	v_mov_b32_e32 v5, v14
	v_pk_mul_f32 v[48:49], v[2:3], v[4:5]
	v_mov_b32_e32 v5, v15
	v_add_f32_e32 v2, v48, v49
	v_mul_f32_e32 v13, v11, v2
	v_mov_b32_e32 v2, v57
	v_pk_mul_f32 v[14:15], v[2:3], v[4:5]
	s_nop 0
	v_add_f32_e32 v2, v14, v15
	v_mul_f32_e32 v50, v11, v2
	v_mov_b32_e32 v2, v58
	s_waitcnt lgkmcnt(0)
	ds_read2st64_b32 v[14:15], v12 offset0:28 offset1:29
	v_mov_b32_e32 v5, v246
	v_pk_mul_f32 v[48:49], v[2:3], v[4:5]
	v_mov_b32_e32 v5, v247
	v_add_f32_e32 v2, v48, v49
	v_mul_f32_e32 v48, v11, v2
	v_mov_b32_e32 v2, v59
	v_pk_mul_f32 v[246:247], v[2:3], v[4:5]
	s_nop 0
	v_add_f32_e32 v2, v246, v247
	v_mul_f32_e32 v2, v11, v2
	v_cvt_pk_bf16_f32 v246, v13, v50
	v_cvt_pk_bf16_f32 v247, v48, v2
	global_store_dwordx2 v[8:9], v[246:247], off offset:224
	v_mov_b32_e32 v2, v60
	s_waitcnt lgkmcnt(0)
	ds_read2st64_b32 v[246:247], v12 offset0:30 offset1:31
	v_mov_b32_e32 v5, v14
	v_pk_mul_f32 v[48:49], v[2:3], v[4:5]
	v_mov_b32_e32 v5, v15
	v_add_f32_e32 v2, v48, v49
	v_mul_f32_e32 v13, v11, v2
	v_mov_b32_e32 v2, v61
	v_pk_mul_f32 v[14:15], v[2:3], v[4:5]
	s_nop 0
	v_add_f32_e32 v2, v14, v15
	v_mul_f32_e32 v50, v11, v2
	v_mov_b32_e32 v2, v62
	s_waitcnt lgkmcnt(0)
	v_mov_b32_e32 v5, v246
	v_pk_mul_f32 v[48:49], v[2:3], v[4:5]
	v_mov_b32_e32 v5, v247
	v_add_f32_e32 v2, v48, v49
	v_mul_f32_e32 v48, v11, v2
	v_mov_b32_e32 v2, v63
	v_pk_mul_f32 v[246:247], v[2:3], v[4:5]
	s_nop 0
	v_add_f32_e32 v2, v246, v247
	v_mul_f32_e32 v2, v11, v2
	v_cvt_pk_bf16_f32 v246, v13, v50
	v_cvt_pk_bf16_f32 v247, v48, v2
	global_store_dwordx2 v[8:9], v[246:247], off offset:240
	s_cbranch_execz .LBB0_681

; __device__ __forceinline__ float fast_exp2(float x) { return __builtin_amdgcn_exp2f(x); }
; template <int DQ, int TYPE>
; __device__ __forceinline__ void attn_item(PP p, int layer, int b, int h, int qt, char* lds, const int tid_, unsigned* next_ctr, volatile XLAS unsigned* slot) {
;     ...
;     unsigned nxt_item = 0; if (tid_ == 0) nxt_item = atomicAdd(next_ctr, 1u);
;     l_run += __shfl_xor(l_run, 32);
;     float* mrg = (float*)lds;
;     {
;         float* mp = mrg + (size_t)((qg * 2 + kh) * 34) * 64 + lane;
;         if (kh == 0) {
; #pragma unroll
;             for (int t2 = 0; t2 < 2; ++t2)
; #pragma unroll
;                 for (int i = 0; i < 16; ++i) mp[(t2 * 16 + i) * 64] = O[2 + t2][i];
;         } else {
; #pragma unroll
;             for (int t2 = 0; t2 < 2; ++t2)
; #pragma unroll
;                 for (int i = 0; i < 16; ++i) mp[(t2 * 16 + i) * 64] = O[t2][i];
;         }
;         mp[32 * 64] = m_run; mp[33 * 64] = l_run;
;     }
;     __syncthreads();
;     {
;         const float* mp = mrg + (size_t)((qg * 2 + (kh ^ 1)) * 34) * 64 + lane;
;         const float m1 = mp[32 * 64], l1 = mp[33 * 64];
;         const float mt = fmaxf(m_run, m1);
;         const float a0 = fast_exp2(m_run - mt), a1 = fast_exp2(m1 - mt);
;         const float inv = 1.0f / (l_run * a0 + l1 * a1);
.LBB0_653:
	s_or_b64 exec, exec, s[12:13]
	s_load_dwordx2 s[14:15], s[0:1], 0x98
	s_lshl_b32 s12, s56, 12
	v_and_b32_e32 v67, 64, v224
	v_xor_b32_e32 v66, 32, v224
	v_add_u32_e32 v67, 64, v67
	s_waitcnt lgkmcnt(0)
	s_add_u32 s12, s14, s12
	s_addc_u32 s13, s15, 0
	s_lshl_b32 s14, s55, 1
	s_add_u32 s12, s12, s14
	v_cmp_lt_i32_e32 vcc, v66, v67
	s_addc_u32 s13, s13, 0
	s_lshl_b32 s14, s81, 1
	v_cndmask_b32_e32 v66, v224, v66, vcc
	s_add_i32 s15, s14, s54
	v_lshlrev_b32_e32 v66, 2, v66
	s_mulk_i32 s15, 0x2200
	ds_bpermute_b32 v66, v66, v164
	s_add_i32 s15, s15, 16
	v_lshlrev_b32_e32 v67, 2, v183
	v_add_u32_e32 v68, s15, v67
	s_xor_b32 s15, s54, 1
	s_add_i32 s14, s14, s15
	s_mulk_i32 s14, 0x2200
	v_cndmask_b32_e64 v76, v27, v59, s[52:53]
	s_waitcnt vmcnt(3)
	v_cndmask_b32_e64 v84, v19, v51, s[52:53]
	v_cndmask_b32_e64 v85, v18, v50, s[52:53]
	s_add_i32 s14, s14, 16
	s_waitcnt lgkmcnt(0)
	v_add_f32_e32 v66, v164, v66
	v_cndmask_b32_e64 v69, v33, v65, s[52:53]
	v_cndmask_b32_e64 v70, v32, v64, s[52:53]
	v_cndmask_b32_e64 v71, v31, v63, s[52:53]
	v_cndmask_b32_e64 v72, v30, v62, s[52:53]
	v_cndmask_b32_e64 v73, v29, v61, s[52:53]
	v_cndmask_b32_e64 v75, v28, v60, s[52:53]
	v_cndmask_b32_e64 v77, v26, v58, s[52:53]
	v_cndmask_b32_e64 v78, v25, v57, s[52:53]
	v_cndmask_b32_e64 v79, v24, v56, s[52:53]
	v_cndmask_b32_e64 v80, v23, v55, s[52:53]
	v_cndmask_b32_e64 v81, v22, v54, s[52:53]
	v_cndmask_b32_e64 v82, v21, v53, s[52:53]
	v_cndmask_b32_e64 v83, v20, v52, s[52:53]
	s_waitcnt vmcnt(2)
	v_cndmask_b32_e64 v86, v17, v49, s[52:53]
	v_cndmask_b32_e64 v87, v16, v48, s[52:53]
	v_cndmask_b32_e64 v88, v15, v47, s[52:53]
	v_cndmask_b32_e64 v89, v14, v46, s[52:53]
	v_cndmask_b32_e64 v90, v13, v45, s[52:53]
	v_cndmask_b32_e64 v91, v12, v44, s[52:53]
	v_cndmask_b32_e64 v92, v11, v43, s[52:53]
	v_cndmask_b32_e64 v93, v10, v42, s[52:53]
	v_cndmask_b32_e64 v94, v9, v41, s[52:53]
	v_cndmask_b32_e64 v95, v8, v40, s[52:53]
	v_cndmask_b32_e64 v96, v7, v39, s[52:53]
	v_cndmask_b32_e64 v97, v6, v38, s[52:53]
	v_cndmask_b32_e64 v98, v5, v37, s[52:53]
	v_cndmask_b32_e64 v99, v4, v36, s[52:53]
	v_cndmask_b32_e64 v100, v3, v35, s[52:53]
	v_cndmask_b32_e64 v101, v2, v34, s[52:53]
	ds_write2st64_b32 v68, v85, v84 offset1:1
	ds_write2st64_b32 v68, v83, v82 offset0:2 offset1:3
	ds_write2st64_b32 v68, v81, v80 offset0:4 offset1:5
	ds_write2st64_b32 v68, v79, v78 offset0:6 offset1:7
	ds_write2st64_b32 v68, v77, v76 offset0:8 offset1:9
	ds_write2st64_b32 v68, v75, v73 offset0:10 offset1:11
	ds_write2st64_b32 v68, v72, v71 offset0:12 offset1:13
	ds_write2st64_b32 v68, v70, v69 offset0:14 offset1:15
	ds_write2st64_b32 v68, v101, v100 offset0:16 offset1:17
	ds_write2st64_b32 v68, v99, v98 offset0:18 offset1:19
	ds_write2st64_b32 v68, v97, v96 offset0:20 offset1:21
	ds_write2st64_b32 v68, v95, v94 offset0:22 offset1:23
	ds_write2st64_b32 v68, v93, v92 offset0:24 offset1:25
	ds_write2st64_b32 v68, v91, v90 offset0:26 offset1:27
	ds_write2st64_b32 v68, v89, v88 offset0:28 offset1:29
	ds_write2st64_b32 v68, v87, v86 offset0:30 offset1:31
	ds_write2st64_b32 v68, v165, v66 offset0:32 offset1:33
	v_add_u32_e32 v76, s14, v67
	s_waitcnt lgkmcnt(0)
	s_barrier
	ds_read2st64_b32 v[68:69], v76 offset0:32 offset1:33
	v_max_f32_e32 v70, v165, v165
	s_waitcnt lgkmcnt(0)
	v_max_f32_e32 v67, v68, v68
	v_max_f32_e32 v67, v70, v67
	v_sub_f32_e32 v70, v165, v67
	v_sub_f32_e32 v67, v68, v67
	v_exp_f32_e32 v67, v67
	v_exp_f32_e32 v68, v70
	v_mul_f32_e32 v69, v69, v67
	v_fmac_f32_e32 v69, v66, v68
	v_div_scale_f32 v66, s[14:15], v69, v69, 1.0
	v_rcp_f32_e32 v70, v66
	s_nop 0
	v_fma_f32 v71, -v66, v70, 1.0
	v_fmac_f32_e32 v70, v71, v70
	v_div_scale_f32 v71, vcc, 1.0, v69, 1.0
	v_mul_f32_e32 v72, v71, v70
	v_fma_f32 v73, -v66, v72, v71
	v_fmac_f32_e32 v72, v73, v70
	v_fma_f32 v66, -v66, v72, v71
	v_div_fmas_f32 v66, v66, v70, v72
	v_lshlrev_b64 v[70:71], 12, v[0:1]
	v_lshl_add_u64 v[70:71], s[12:13], 0, v[70:71]
	s_mov_b64 s[12:13], 0x27388400
	v_div_fixup_f32 v75, v66, v69, 1.0
	v_lshl_add_u64 v[70:71], v[70:71], 0, s[12:13]
	s_mov_b64 s[12:13], -1
	s_andn2_b64 vcc, exec, s[8:9]
	v_lshlrev_b32_e32 v0, 1, v147
	s_cbranch_vccnz .LBB0_682
	ds_read2st64_b32 v[78:79], v76 offset1:1
	v_mov_b32_e32 v66, v50
	v_lshl_add_u64 v[72:73], v[70:71], 0, v[0:1]
	s_waitcnt lgkmcnt(0)
	v_mov_b32_e32 v69, v78
	v_pk_mul_f32 v[80:81], v[66:67], v[68:69]
	v_mov_b32_e32 v66, v51
	v_add_f32_e32 v50, v80, v81
	v_mov_b32_e32 v69, v79
	v_mul_f32_e32 v77, v75, v50
	v_pk_mul_f32 v[50:51], v[66:67], v[68:69]
	v_mov_b32_e32 v66, v52
	v_add_f32_e32 v50, v50, v51
	v_mul_f32_e32 v80, v75, v50
	ds_read2st64_b32 v[50:51], v76 offset0:2 offset1:3
	s_waitcnt lgkmcnt(0)
	ds_read2st64_b32 v[246:247], v76 offset0:4 offset1:5
	v_mov_b32_e32 v69, v50
	v_pk_mul_f32 v[78:79], v[66:67], v[68:69]
	v_mov_b32_e32 v66, v53
	v_add_f32_e32 v50, v78, v79
	v_mov_b32_e32 v69, v51
	v_mul_f32_e32 v52, v75, v50
	v_pk_mul_f32 v[50:51], v[66:67], v[68:69]
	v_mov_b32_e32 v66, v54
	v_add_f32_e32 v50, v50, v51
	v_mul_f32_e32 v51, v75, v50
	v_cvt_pk_bf16_f32 v50, v77, v80
	v_cvt_pk_bf16_f32 v51, v52, v51
	global_store_dwordx2 v[72:73], v[50:51], off offset:128
	s_waitcnt lgkmcnt(0)
	ds_read2st64_b32 v[50:51], v76 offset0:6 offset1:7
	v_mov_b32_e32 v69, v246
	v_pk_mul_f32 v[52:53], v[66:67], v[68:69]
	v_mov_b32_e32 v66, v55
	v_add_f32_e32 v246, v52, v53
	v_mov_b32_e32 v69, v247
	v_mul_f32_e32 v54, v75, v246
	v_pk_mul_f32 v[246:247], v[66:67], v[68:69]
	v_mov_b32_e32 v66, v56
	v_add_f32_e32 v246, v246, v247
	v_mul_f32_e32 v55, v75, v246
	s_waitcnt lgkmcnt(0)
; template <int DQ, int TYPE>
; __device__ __forceinline__ void attn_item(PP p, int layer, int b, int h, int qt, char* lds, const int tid_, unsigned* next_ctr, volatile XLAS unsigned* slot) {
;     ...
;         if (kh == 0) A_MERGE(0); else A_MERGE(2);
	ds_read2st64_b32 v[246:247], v76 offset0:8 offset1:9
	v_mov_b32_e32 v69, v50
	v_pk_mul_f32 v[52:53], v[66:67], v[68:69]
	v_mov_b32_e32 v66, v57
	v_add_f32_e32 v50, v52, v53
	v_mov_b32_e32 v69, v51
	v_mul_f32_e32 v52, v75, v50
	v_pk_mul_f32 v[50:51], v[66:67], v[68:69]
	v_mov_b32_e32 v66, v58
	v_add_f32_e32 v50, v50, v51
	v_mul_f32_e32 v51, v75, v50
	v_cvt_pk_bf16_f32 v50, v54, v55
	v_cvt_pk_bf16_f32 v51, v52, v51
	global_store_dwordx2 v[72:73], v[50:51], off offset:144
	s_waitcnt lgkmcnt(0)
	ds_read2st64_b32 v[50:51], v76 offset0:10 offset1:11
	v_mov_b32_e32 v69, v246
	v_pk_mul_f32 v[52:53], v[66:67], v[68:69]
	v_mov_b32_e32 v66, v59
	v_add_f32_e32 v246, v52, v53
	v_mov_b32_e32 v69, v247
	v_mul_f32_e32 v54, v75, v246
	v_pk_mul_f32 v[246:247], v[66:67], v[68:69]
	v_mov_b32_e32 v66, v60
	v_add_f32_e32 v246, v246, v247
	v_mul_f32_e32 v55, v75, v246
	s_waitcnt lgkmcnt(0)
	ds_read2st64_b32 v[246:247], v76 offset0:12 offset1:13
	v_mov_b32_e32 v69, v50
	v_pk_mul_f32 v[52:53], v[66:67], v[68:69]
	v_mov_b32_e32 v66, v61
	v_add_f32_e32 v50, v52, v53
	v_mov_b32_e32 v69, v51
	v_mul_f32_e32 v52, v75, v50
	v_pk_mul_f32 v[50:51], v[66:67], v[68:69]
	v_mov_b32_e32 v66, v62
	v_add_f32_e32 v50, v50, v51
	v_mul_f32_e32 v51, v75, v50
	v_cvt_pk_bf16_f32 v50, v54, v55
	v_cvt_pk_bf16_f32 v51, v52, v51
	global_store_dwordx2 v[72:73], v[50:51], off offset:160
	s_waitcnt lgkmcnt(0)
	ds_read2st64_b32 v[50:51], v76 offset0:14 offset1:15
	v_mov_b32_e32 v69, v246
	v_pk_mul_f32 v[52:53], v[66:67], v[68:69]
	v_mov_b32_e32 v66, v63
	v_add_f32_e32 v246, v52, v53
	v_mov_b32_e32 v69, v247
	v_mul_f32_e32 v54, v75, v246
	v_pk_mul_f32 v[246:247], v[66:67], v[68:69]
	v_mov_b32_e32 v66, v64
	v_add_f32_e32 v246, v246, v247
	v_mul_f32_e32 v55, v75, v246
	s_waitcnt lgkmcnt(0)
	ds_read2st64_b32 v[246:247], v76 offset0:16 offset1:17
	v_mov_b32_e32 v69, v50
	v_pk_mul_f32 v[52:53], v[66:67], v[68:69]
	v_mov_b32_e32 v66, v65
	v_add_f32_e32 v50, v52, v53
	v_mov_b32_e32 v69, v51
	v_mul_f32_e32 v52, v75, v50
	v_pk_mul_f32 v[50:51], v[66:67], v[68:69]
	v_mov_b32_e32 v66, v34
	v_add_f32_e32 v50, v50, v51
	v_mul_f32_e32 v51, v75, v50
	v_cvt_pk_bf16_f32 v50, v54, v55
	v_cvt_pk_bf16_f32 v51, v52, v51
	global_store_dwordx2 v[72:73], v[50:51], off offset:176
	s_waitcnt lgkmcnt(0)
	v_mov_b32_e32 v69, v246
	v_pk_mul_f32 v[52:53], v[66:67], v[68:69]
	v_mov_b32_e32 v66, v35
	v_add_f32_e32 v34, v52, v53
	v_mov_b32_e32 v69, v247
	v_mul_f32_e32 v52, v75, v34
	v_pk_mul_f32 v[34:35], v[66:67], v[68:69]
	v_mov_b32_e32 v66, v36
	v_add_f32_e32 v34, v34, v35
	v_mul_f32_e32 v53, v75, v34
	ds_read2st64_b32 v[34:35], v76 offset0:18 offset1:19
	s_waitcnt lgkmcnt(0)
	ds_read2st64_b32 v[246:247], v76 offset0:20 offset1:21
	v_mov_b32_e32 v69, v34
	v_pk_mul_f32 v[50:51], v[66:67], v[68:69]
	v_mov_b32_e32 v66, v37
	v_add_f32_e32 v34, v50, v51
	v_mov_b32_e32 v69, v35
	v_mul_f32_e32 v36, v75, v34
	v_pk_mul_f32 v[34:35], v[66:67], v[68:69]
	v_mov_b32_e32 v66, v38
	v_add_f32_e32 v34, v34, v35
	v_mul_f32_e32 v35, v75, v34
	v_cvt_pk_bf16_f32 v34, v52, v53
	v_cvt_pk_bf16_f32 v35, v36, v35
	global_store_dwordx2 v[72:73], v[34:35], off offset:192
	s_waitcnt lgkmcnt(0)
	ds_read2st64_b32 v[34:35], v76 offset0:22 offset1:23
	v_mov_b32_e32 v69, v246
	v_pk_mul_f32 v[36:37], v[66:67], v[68:69]
	v_mov_b32_e32 v66, v39
	v_add_f32_e32 v246, v36, v37
	v_mov_b32_e32 v69, v247
	v_mul_f32_e32 v38, v75, v246
	v_pk_mul_f32 v[246:247], v[66:67], v[68:69]
	v_mov_b32_e32 v66, v40
	v_add_f32_e32 v246, v246, v247
	v_mul_f32_e32 v39, v75, v246
	s_waitcnt lgkmcnt(0)
	ds_read2st64_b32 v[246:247], v76 offset0:24 offset1:25
	v_mov_b32_e32 v69, v34
	v_pk_mul_f32 v[36:37], v[66:67], v[68:69]
	v_mov_b32_e32 v66, v41
	v_add_f32_e32 v34, v36, v37
	v_mov_b32_e32 v69, v35
	v_mul_f32_e32 v36, v75, v34
	v_pk_mul_f32 v[34:35], v[66:67], v[68:69]
	v_mov_b32_e32 v66, v42
	v_add_f32_e32 v34, v34, v35
	v_mul_f32_e32 v35, v75, v34
	v_cvt_pk_bf16_f32 v34, v38, v39
	v_cvt_pk_bf16_f32 v35, v36, v35
	global_store_dwordx2 v[72:73], v[34:35], off offset:208
	s_waitcnt lgkmcnt(0)
	ds_read2st64_b32 v[34:35], v76 offset0:26 offset1:27
	v_mov_b32_e32 v69, v246
	v_pk_mul_f32 v[36:37], v[66:67], v[68:69]
	v_mov_b32_e32 v66, v43
	v_add_f32_e32 v246, v36, v37
	v_mov_b32_e32 v69, v247
	v_mul_f32_e32 v38, v75, v246
	v_pk_mul_f32 v[246:247], v[66:67], v[68:69]
	v_mov_b32_e32 v66, v44
	v_add_f32_e32 v246, v246, v247
	v_mul_f32_e32 v39, v75, v246
	s_waitcnt lgkmcnt(0)
	ds_read2st64_b32 v[246:247], v76 offset0:28 offset1:29
	v_mov_b32_e32 v69, v34
	v_pk_mul_f32 v[36:37], v[66:67], v[68:69]
	v_mov_b32_e32 v66, v45
	v_add_f32_e32 v34, v36, v37
	v_mov_b32_e32 v69, v35
	v_mul_f32_e32 v36, v75, v34
	v_pk_mul_f32 v[34:35], v[66:67], v[68:69]
	v_mov_b32_e32 v66, v46
	v_add_f32_e32 v34, v34, v35
	v_mul_f32_e32 v35, v75, v34
	v_cvt_pk_bf16_f32 v34, v38, v39
	v_cvt_pk_bf16_f32 v35, v36, v35
	global_store_dwordx2 v[72:73], v[34:35], off offset:224
	s_waitcnt lgkmcnt(0)
	ds_read2st64_b32 v[34:35], v76 offset0:30 offset1:31
	v_mov_b32_e32 v69, v246
	v_pk_mul_f32 v[36:37], v[66:67], v[68:69]
	v_mov_b32_e32 v66, v47
	v_add_f32_e32 v246, v36, v37
	v_mov_b32_e32 v69, v247
	v_mul_f32_e32 v38, v75, v246
	v_pk_mul_f32 v[246:247], v[66:67], v[68:69]
	v_mov_b32_e32 v66, v48
	v_add_f32_e32 v246, v246, v247
	v_mul_f32_e32 v39, v75, v246
	s_waitcnt lgkmcnt(0)
	v_mov_b32_e32 v69, v34
	v_pk_mul_f32 v[36:37], v[66:67], v[68:69]
	v_mov_b32_e32 v66, v49
	v_add_f32_e32 v34, v36, v37
	v_mov_b32_e32 v69, v35
	v_mul_f32_e32 v36, v75, v34
	v_pk_mul_f32 v[34:35], v[66:67], v[68:69]
	s_nop 0
	v_add_f32_e32 v34, v34, v35
	v_mul_f32_e32 v35, v75, v34
	v_cvt_pk_bf16_f32 v34, v38, v39
	v_cvt_pk_bf16_f32 v35, v36, v35
	global_store_dwordx2 v[72:73], v[34:35], off offset:240
	s_cbranch_execz .LBB0_683

; __device__ __forceinline__ float fast_exp2(float x) { return __builtin_amdgcn_exp2f(x); }
; template <int DQ, int TYPE>
; __device__ __forceinline__ void attn_item(PP p, int layer, int b, int h, int qt, char* lds, const int tid_, unsigned* next_ctr, volatile XLAS unsigned* slot) {
;     ...
;     unsigned nxt_item = 0; if (tid_ == 0) nxt_item = atomicAdd(next_ctr, 1u);
;     l_run += __shfl_xor(l_run, 32);
;     float* mrg = (float*)lds;
;     {
;         float* mp = mrg + (size_t)((qg * 2 + kh) * 34) * 64 + lane;
;         if (kh == 0) {
; #pragma unroll
;             for (int t2 = 0; t2 < 2; ++t2)
; #pragma unroll
;                 for (int i = 0; i < 16; ++i) mp[(t2 * 16 + i) * 64] = O[2 + t2][i];
;         } else {
; #pragma unroll
;             for (int t2 = 0; t2 < 2; ++t2)
; #pragma unroll
;                 for (int i = 0; i < 16; ++i) mp[(t2 * 16 + i) * 64] = O[t2][i];
;         }
;         mp[32 * 64] = m_run; mp[33 * 64] = l_run;
;     }
;     __syncthreads();
;     {
;         const float* mp = mrg + (size_t)((qg * 2 + (kh ^ 1)) * 34) * 64 + lane;
;         const float m1 = mp[32 * 64], l1 = mp[33 * 64];
;         const float mt = fmaxf(m_run, m1);
;         const float a0 = fast_exp2(m_run - mt), a1 = fast_exp2(m1 - mt);
;         const float inv = 1.0f / (l_run * a0 + l1 * a1);
.LBB0_677:
	s_or_b64 exec, exec, s[12:13]
	s_lshl_b32 s12, s55, 12
	s_add_u32 s12, s38, s12
	v_and_b32_e32 v66, 64, v224
	s_addc_u32 s13, s39, 0
	s_lshl_b32 s14, s54, 8
	v_xor_b32_e32 v0, 32, v224
	v_add_u32_e32 v66, 64, v66
	s_add_u32 s12, s12, s14
	v_cmp_lt_i32_e32 vcc, v0, v66
	s_addc_u32 s13, s13, 0
	s_lshl_b32 s14, s48, 1
	v_cndmask_b32_e32 v0, v224, v0, vcc
	s_add_i32 s15, s14, s56
	v_lshlrev_b32_e32 v0, 2, v0
	s_mulk_i32 s15, 0x2200
	ds_bpermute_b32 v0, v0, v199
	s_add_i32 s15, s15, 16
	v_lshlrev_b32_e32 v66, 2, v183
	v_add_u32_e32 v67, s15, v66
	s_xor_b32 s15, s56, 1
	s_add_i32 s14, s14, s15
	s_mulk_i32 s14, 0x2200
	v_cndmask_b32_e64 v76, v26, v58, s[52:53]
	v_cndmask_b32_e64 v83, v19, v51, s[52:53]
	v_cndmask_b32_e64 v84, v18, v50, s[52:53]
	s_add_i32 s14, s14, 16
	s_waitcnt lgkmcnt(0)
	v_add_f32_e32 v0, v199, v0
	v_cndmask_b32_e64 v68, v33, v65, s[52:53]
	v_cndmask_b32_e64 v69, v32, v64, s[52:53]
	v_cndmask_b32_e64 v70, v31, v63, s[52:53]
	v_cndmask_b32_e64 v71, v30, v62, s[52:53]
	v_cndmask_b32_e64 v72, v29, v61, s[52:53]
	v_cndmask_b32_e64 v73, v28, v60, s[52:53]
	v_cndmask_b32_e64 v75, v27, v59, s[52:53]
	v_cndmask_b32_e64 v77, v25, v57, s[52:53]
	v_cndmask_b32_e64 v78, v24, v56, s[52:53]
	v_cndmask_b32_e64 v79, v23, v55, s[52:53]
	v_cndmask_b32_e64 v80, v22, v54, s[52:53]
	v_cndmask_b32_e64 v81, v21, v53, s[52:53]
	v_cndmask_b32_e64 v82, v20, v52, s[52:53]
	v_cndmask_b32_e64 v85, v17, v49, s[52:53]
	s_waitcnt vmcnt(4)
	v_cndmask_b32_e64 v86, v16, v48, s[52:53]
	v_cndmask_b32_e64 v87, v15, v47, s[52:53]
	v_cndmask_b32_e64 v88, v14, v46, s[52:53]
	v_cndmask_b32_e64 v89, v13, v45, s[52:53]
	s_waitcnt vmcnt(3)
	v_cndmask_b32_e64 v90, v12, v44, s[52:53]
	v_cndmask_b32_e64 v91, v11, v43, s[52:53]
	v_cndmask_b32_e64 v92, v10, v42, s[52:53]
	v_cndmask_b32_e64 v93, v9, v41, s[52:53]
	v_cndmask_b32_e64 v94, v8, v40, s[52:53]
	v_cndmask_b32_e64 v95, v7, v39, s[52:53]
	v_cndmask_b32_e64 v96, v6, v38, s[52:53]
	v_cndmask_b32_e64 v97, v5, v37, s[52:53]
	v_cndmask_b32_e64 v98, v4, v36, s[52:53]
	v_cndmask_b32_e64 v99, v3, v35, s[52:53]
	v_cndmask_b32_e64 v100, v2, v34, s[52:53]
	ds_write2st64_b32 v67, v84, v83 offset1:1
	ds_write2st64_b32 v67, v82, v81 offset0:2 offset1:3
	ds_write2st64_b32 v67, v80, v79 offset0:4 offset1:5
	ds_write2st64_b32 v67, v78, v77 offset0:6 offset1:7
	ds_write2st64_b32 v67, v76, v75 offset0:8 offset1:9
	ds_write2st64_b32 v67, v73, v72 offset0:10 offset1:11
	ds_write2st64_b32 v67, v71, v70 offset0:12 offset1:13
	ds_write2st64_b32 v67, v69, v68 offset0:14 offset1:15
	ds_write2st64_b32 v67, v100, v99 offset0:16 offset1:17
	ds_write2st64_b32 v67, v98, v97 offset0:18 offset1:19
	ds_write2st64_b32 v67, v96, v95 offset0:20 offset1:21
	ds_write2st64_b32 v67, v94, v93 offset0:22 offset1:23
	ds_write2st64_b32 v67, v92, v91 offset0:24 offset1:25
	ds_write2st64_b32 v67, v90, v89 offset0:26 offset1:27
	ds_write2st64_b32 v67, v88, v87 offset0:28 offset1:29
	ds_write2st64_b32 v67, v86, v85 offset0:30 offset1:31
	ds_write2st64_b32 v67, v200, v0 offset0:32 offset1:33
	v_add_u32_e32 v76, s14, v66
	s_waitcnt lgkmcnt(0)
	s_barrier
	ds_read2st64_b32 v[68:69], v76 offset0:32 offset1:33
	v_max_f32_e32 v67, v200, v200
	s_waitcnt lgkmcnt(0)
	v_max_f32_e32 v66, v68, v68
	v_max_f32_e32 v66, v67, v66
	v_sub_f32_e32 v70, v200, v66
	v_sub_f32_e32 v66, v68, v66
	v_exp_f32_e32 v67, v66
	v_exp_f32_e32 v68, v70
	v_mul_f32_e32 v66, v69, v67
	v_fmac_f32_e32 v66, v0, v68
	v_div_scale_f32 v0, s[14:15], v66, v66, 1.0
	v_rcp_f32_e32 v69, v0
	s_nop 0
	v_fma_f32 v70, -v0, v69, 1.0
	v_fmac_f32_e32 v69, v70, v69
	v_div_scale_f32 v70, vcc, 1.0, v66, 1.0
	v_mul_f32_e32 v71, v70, v69
	v_fma_f32 v72, -v0, v71, v70
	v_fmac_f32_e32 v71, v72, v69
	v_fma_f32 v0, -v0, v71, v70
	v_div_fmas_f32 v0, v0, v69, v71
	v_lshlrev_b64 v[70:71], 12, v[172:173]
	v_div_fixup_f32 v75, v0, v66, 1.0
	v_lshl_add_u64 v[70:71], s[12:13], 0, v[70:71]
	s_mov_b64 s[12:13], -1
	s_andn2_b64 vcc, exec, s[8:9]
	v_lshlrev_b32_e32 v0, 1, v187
	s_cbranch_vccnz .LBB0_684
	ds_read2st64_b32 v[78:79], v76 offset1:1
	v_mov_b32_e32 v66, v50
	v_lshl_add_u64 v[72:73], v[70:71], 0, v[0:1]
	s_waitcnt lgkmcnt(0)
	v_mov_b32_e32 v69, v78
	v_pk_mul_f32 v[80:81], v[66:67], v[68:69]
	v_mov_b32_e32 v66, v51
	v_add_f32_e32 v50, v80, v81
	v_mov_b32_e32 v69, v79
	v_mul_f32_e32 v77, v75, v50
	v_pk_mul_f32 v[50:51], v[66:67], v[68:69]
	v_mov_b32_e32 v66, v52
	v_add_f32_e32 v50, v50, v51
	v_mul_f32_e32 v80, v75, v50
	ds_read2st64_b32 v[50:51], v76 offset0:2 offset1:3
	s_waitcnt lgkmcnt(0)
	ds_read2st64_b32 v[246:247], v76 offset0:4 offset1:5
	v_mov_b32_e32 v69, v50
	v_pk_mul_f32 v[78:79], v[66:67], v[68:69]
	v_mov_b32_e32 v66, v53
	v_add_f32_e32 v50, v78, v79
	v_mov_b32_e32 v69, v51
	v_mul_f32_e32 v52, v75, v50
	v_pk_mul_f32 v[50:51], v[66:67], v[68:69]
	v_mov_b32_e32 v66, v54
	v_add_f32_e32 v50, v50, v51
	v_mul_f32_e32 v51, v75, v50
	v_cvt_pk_bf16_f32 v50, v77, v80
	v_cvt_pk_bf16_f32 v51, v52, v51
	global_store_dwordx2 v[72:73], v[50:51], off offset:128
	s_waitcnt lgkmcnt(0)
	ds_read2st64_b32 v[50:51], v76 offset0:6 offset1:7
	v_mov_b32_e32 v69, v246
	v_pk_mul_f32 v[52:53], v[66:67], v[68:69]
	v_mov_b32_e32 v66, v55
	v_add_f32_e32 v246, v52, v53
	v_mov_b32_e32 v69, v247
	v_mul_f32_e32 v54, v75, v246
	v_pk_mul_f32 v[246:247], v[66:67], v[68:69]
	v_mov_b32_e32 v66, v56
	v_add_f32_e32 v246, v246, v247
	v_mul_f32_e32 v55, v75, v246
	s_waitcnt lgkmcnt(0)
; template <int DQ, int TYPE>
; __device__ __forceinline__ void attn_item(PP p, int layer, int b, int h, int qt, char* lds, const int tid_, unsigned* next_ctr, volatile XLAS unsigned* slot) {
;     ...
;         if (kh == 0) A_MERGE(0); else A_MERGE(2);
	ds_read2st64_b32 v[246:247], v76 offset0:8 offset1:9
	v_mov_b32_e32 v69, v50
	v_pk_mul_f32 v[52:53], v[66:67], v[68:69]
	v_mov_b32_e32 v66, v57
	v_add_f32_e32 v50, v52, v53
	v_mov_b32_e32 v69, v51
	v_mul_f32_e32 v52, v75, v50
	v_pk_mul_f32 v[50:51], v[66:67], v[68:69]
	v_mov_b32_e32 v66, v58
	v_add_f32_e32 v50, v50, v51
	v_mul_f32_e32 v51, v75, v50
	v_cvt_pk_bf16_f32 v50, v54, v55
	v_cvt_pk_bf16_f32 v51, v52, v51
	global_store_dwordx2 v[72:73], v[50:51], off offset:144
	s_waitcnt lgkmcnt(0)
	ds_read2st64_b32 v[50:51], v76 offset0:10 offset1:11
	v_mov_b32_e32 v69, v246
	v_pk_mul_f32 v[52:53], v[66:67], v[68:69]
	v_mov_b32_e32 v66, v59
	v_add_f32_e32 v246, v52, v53
	v_mov_b32_e32 v69, v247
	v_mul_f32_e32 v54, v75, v246
	v_pk_mul_f32 v[246:247], v[66:67], v[68:69]
	v_mov_b32_e32 v66, v60
	v_add_f32_e32 v246, v246, v247
	v_mul_f32_e32 v55, v75, v246
	s_waitcnt lgkmcnt(0)
	ds_read2st64_b32 v[246:247], v76 offset0:12 offset1:13
	v_mov_b32_e32 v69, v50
	v_pk_mul_f32 v[52:53], v[66:67], v[68:69]
	v_mov_b32_e32 v66, v61
	v_add_f32_e32 v50, v52, v53
	v_mov_b32_e32 v69, v51
	v_mul_f32_e32 v52, v75, v50
	v_pk_mul_f32 v[50:51], v[66:67], v[68:69]
	v_mov_b32_e32 v66, v62
	v_add_f32_e32 v50, v50, v51
	v_mul_f32_e32 v51, v75, v50
	v_cvt_pk_bf16_f32 v50, v54, v55
	v_cvt_pk_bf16_f32 v51, v52, v51
	global_store_dwordx2 v[72:73], v[50:51], off offset:160
	s_waitcnt lgkmcnt(0)
	ds_read2st64_b32 v[50:51], v76 offset0:14 offset1:15
	v_mov_b32_e32 v69, v246
	v_pk_mul_f32 v[52:53], v[66:67], v[68:69]
	v_mov_b32_e32 v66, v63
	v_add_f32_e32 v246, v52, v53
	v_mov_b32_e32 v69, v247
	v_mul_f32_e32 v54, v75, v246
	v_pk_mul_f32 v[246:247], v[66:67], v[68:69]
	v_mov_b32_e32 v66, v64
	v_add_f32_e32 v246, v246, v247
	v_mul_f32_e32 v55, v75, v246
	s_waitcnt lgkmcnt(0)
	ds_read2st64_b32 v[246:247], v76 offset0:16 offset1:17
	v_mov_b32_e32 v69, v50
	v_pk_mul_f32 v[52:53], v[66:67], v[68:69]
	v_mov_b32_e32 v66, v65
	v_add_f32_e32 v50, v52, v53
	v_mov_b32_e32 v69, v51
	v_mul_f32_e32 v52, v75, v50
	v_pk_mul_f32 v[50:51], v[66:67], v[68:69]
	v_mov_b32_e32 v66, v34
	v_add_f32_e32 v50, v50, v51
	v_mul_f32_e32 v51, v75, v50
	v_cvt_pk_bf16_f32 v50, v54, v55
	v_cvt_pk_bf16_f32 v51, v52, v51
	global_store_dwordx2 v[72:73], v[50:51], off offset:176
	s_waitcnt lgkmcnt(0)
	v_mov_b32_e32 v69, v246
	v_pk_mul_f32 v[52:53], v[66:67], v[68:69]
	v_mov_b32_e32 v66, v35
	v_add_f32_e32 v34, v52, v53
	v_mov_b32_e32 v69, v247
	v_mul_f32_e32 v52, v75, v34
	v_pk_mul_f32 v[34:35], v[66:67], v[68:69]
	v_mov_b32_e32 v66, v36
	v_add_f32_e32 v34, v34, v35
	v_mul_f32_e32 v53, v75, v34
	ds_read2st64_b32 v[34:35], v76 offset0:18 offset1:19
	s_waitcnt lgkmcnt(0)
	ds_read2st64_b32 v[246:247], v76 offset0:20 offset1:21
	v_mov_b32_e32 v69, v34
	v_pk_mul_f32 v[50:51], v[66:67], v[68:69]
	v_mov_b32_e32 v66, v37
	v_add_f32_e32 v34, v50, v51
	v_mov_b32_e32 v69, v35
	v_mul_f32_e32 v36, v75, v34
	v_pk_mul_f32 v[34:35], v[66:67], v[68:69]
	v_mov_b32_e32 v66, v38
	v_add_f32_e32 v34, v34, v35
	v_mul_f32_e32 v35, v75, v34
	v_cvt_pk_bf16_f32 v34, v52, v53
	v_cvt_pk_bf16_f32 v35, v36, v35
	global_store_dwordx2 v[72:73], v[34:35], off offset:192
	s_waitcnt lgkmcnt(0)
	ds_read2st64_b32 v[34:35], v76 offset0:22 offset1:23
	v_mov_b32_e32 v69, v246
	v_pk_mul_f32 v[36:37], v[66:67], v[68:69]
	v_mov_b32_e32 v66, v39
	v_add_f32_e32 v246, v36, v37
	v_mov_b32_e32 v69, v247
	v_mul_f32_e32 v38, v75, v246
	v_pk_mul_f32 v[246:247], v[66:67], v[68:69]
	v_mov_b32_e32 v66, v40
	v_add_f32_e32 v246, v246, v247
	v_mul_f32_e32 v39, v75, v246
	s_waitcnt lgkmcnt(0)
	ds_read2st64_b32 v[246:247], v76 offset0:24 offset1:25
	v_mov_b32_e32 v69, v34
	v_pk_mul_f32 v[36:37], v[66:67], v[68:69]
	v_mov_b32_e32 v66, v41
	v_add_f32_e32 v34, v36, v37
	v_mov_b32_e32 v69, v35
	v_mul_f32_e32 v36, v75, v34
	v_pk_mul_f32 v[34:35], v[66:67], v[68:69]
	v_mov_b32_e32 v66, v42
	v_add_f32_e32 v34, v34, v35
	v_mul_f32_e32 v35, v75, v34
	v_cvt_pk_bf16_f32 v34, v38, v39
	v_cvt_pk_bf16_f32 v35, v36, v35
	global_store_dwordx2 v[72:73], v[34:35], off offset:208
	s_waitcnt lgkmcnt(0)
	ds_read2st64_b32 v[34:35], v76 offset0:26 offset1:27
	v_mov_b32_e32 v69, v246
	v_pk_mul_f32 v[36:37], v[66:67], v[68:69]
	v_mov_b32_e32 v66, v43
	v_add_f32_e32 v246, v36, v37
	v_mov_b32_e32 v69, v247
	v_mul_f32_e32 v38, v75, v246
	v_pk_mul_f32 v[246:247], v[66:67], v[68:69]
	v_mov_b32_e32 v66, v44
	v_add_f32_e32 v246, v246, v247
	v_mul_f32_e32 v39, v75, v246
	s_waitcnt lgkmcnt(0)
	ds_read2st64_b32 v[246:247], v76 offset0:28 offset1:29
	v_mov_b32_e32 v69, v34
	v_pk_mul_f32 v[36:37], v[66:67], v[68:69]
	v_mov_b32_e32 v66, v45
	v_add_f32_e32 v34, v36, v37
	v_mov_b32_e32 v69, v35
	v_mul_f32_e32 v36, v75, v34
	v_pk_mul_f32 v[34:35], v[66:67], v[68:69]
	v_mov_b32_e32 v66, v46
	v_add_f32_e32 v34, v34, v35
	v_mul_f32_e32 v35, v75, v34
	v_cvt_pk_bf16_f32 v34, v38, v39
	v_cvt_pk_bf16_f32 v35, v36, v35
	global_store_dwordx2 v[72:73], v[34:35], off offset:224
	s_waitcnt lgkmcnt(0)
	ds_read2st64_b32 v[34:35], v76 offset0:30 offset1:31
	v_mov_b32_e32 v69, v246
	v_pk_mul_f32 v[36:37], v[66:67], v[68:69]
	v_mov_b32_e32 v66, v47
	v_add_f32_e32 v246, v36, v37
	v_mov_b32_e32 v69, v247
	v_mul_f32_e32 v38, v75, v246
	v_pk_mul_f32 v[246:247], v[66:67], v[68:69]
	v_mov_b32_e32 v66, v48
	v_add_f32_e32 v246, v246, v247
	v_mul_f32_e32 v39, v75, v246
	s_waitcnt lgkmcnt(0)
	v_mov_b32_e32 v69, v34
	v_pk_mul_f32 v[36:37], v[66:67], v[68:69]
	v_mov_b32_e32 v66, v49
	v_add_f32_e32 v34, v36, v37
	v_mov_b32_e32 v69, v35
	v_mul_f32_e32 v36, v75, v34
	v_pk_mul_f32 v[34:35], v[66:67], v[68:69]
	s_nop 0
	v_add_f32_e32 v34, v34, v35
	v_mul_f32_e32 v35, v75, v34
	v_cvt_pk_bf16_f32 v34, v38, v39
	v_cvt_pk_bf16_f32 v35, v36, v35
	global_store_dwordx2 v[72:73], v[34:35], off offset:240
	s_cbranch_execz .LBB0_685

; __device__ __forceinline__ float fast_exp2(float x) { return __builtin_amdgcn_exp2f(x); }
; template <int DQ, int TYPE>
; __device__ __forceinline__ void attn_item(PP p, int layer, int b, int h, int qt, char* lds, const int tid_, unsigned* next_ctr, volatile XLAS unsigned* slot) {
;     ...
;         const float* mp = mrg + (size_t)((qg * 2 + (kh ^ 1)) * 34) * 64 + lane;
;         const float m1 = mp[32 * 64], l1 = mp[33 * 64];
;         const float mt = fmaxf(m_run, m1);
;         const float a0 = fast_exp2(m_run - mt), a1 = fast_exp2(m1 - mt);
;         const float inv = 1.0f / (l_run * a0 + l1 * a1);
;         bf16_t* orow = Op + (size_t)qpos * D;
;     ...
;         if (kh == 0) A_MERGE(0); else A_MERGE(2);
.LBB0_681:
	ds_read2st64_b32 v[8:9], v12 offset1:1
	v_mov_b32_e32 v2, v32
	v_lshl_add_u64 v[6:7], v[6:7], 0, v[0:1]
	s_waitcnt lgkmcnt(0)
	ds_read2st64_b32 v[246:247], v12 offset0:2 offset1:3
	v_mov_b32_e32 v5, v8
	v_pk_mul_f32 v[14:15], v[2:3], v[4:5]
	v_mov_b32_e32 v2, v33
	v_mov_b32_e32 v5, v9
	v_pk_mul_f32 v[8:9], v[2:3], v[4:5]
	v_add_f32_e32 v0, v14, v15
	v_add_f32_e32 v2, v8, v9
	v_mul_f32_e32 v13, v11, v2
	v_mov_b32_e32 v2, v34
	v_mul_f32_e32 v0, v11, v0
	s_waitcnt lgkmcnt(0)
	ds_read2st64_b32 v[8:9], v12 offset0:4 offset1:5
	v_mov_b32_e32 v5, v246
	v_pk_mul_f32 v[14:15], v[2:3], v[4:5]
	v_mov_b32_e32 v5, v247
	v_add_f32_e32 v2, v14, v15
	v_mul_f32_e32 v14, v11, v2
	v_mov_b32_e32 v2, v35
	v_pk_mul_f32 v[246:247], v[2:3], v[4:5]
	s_nop 0
	v_add_f32_e32 v2, v246, v247
	v_mul_f32_e32 v2, v11, v2
	v_cvt_pk_bf16_f32 v246, v0, v13
	v_cvt_pk_bf16_f32 v247, v14, v2
	global_store_dwordx2 v[6:7], v[246:247], off
	v_mov_b32_e32 v2, v36
	s_waitcnt lgkmcnt(0)
	ds_read2st64_b32 v[246:247], v12 offset0:6 offset1:7
	v_mov_b32_e32 v5, v8
	v_pk_mul_f32 v[14:15], v[2:3], v[4:5]
	v_mov_b32_e32 v2, v37
	v_mov_b32_e32 v5, v9
	v_pk_mul_f32 v[8:9], v[2:3], v[4:5]
	v_add_f32_e32 v0, v14, v15
	v_add_f32_e32 v2, v8, v9
	v_mul_f32_e32 v13, v11, v2
	v_mov_b32_e32 v2, v38
	v_mul_f32_e32 v0, v11, v0
	s_waitcnt lgkmcnt(0)
	ds_read2st64_b32 v[8:9], v12 offset0:8 offset1:9
	v_mov_b32_e32 v5, v246
	v_pk_mul_f32 v[14:15], v[2:3], v[4:5]
	v_mov_b32_e32 v5, v247
	v_add_f32_e32 v2, v14, v15
	v_mul_f32_e32 v14, v11, v2
	v_mov_b32_e32 v2, v39
	v_pk_mul_f32 v[246:247], v[2:3], v[4:5]
	s_nop 0
	v_add_f32_e32 v2, v246, v247
	v_mul_f32_e32 v2, v11, v2
	v_cvt_pk_bf16_f32 v246, v0, v13
	v_cvt_pk_bf16_f32 v247, v14, v2
	global_store_dwordx2 v[6:7], v[246:247], off offset:16
	v_mov_b32_e32 v2, v40
	s_waitcnt lgkmcnt(0)
	ds_read2st64_b32 v[246:247], v12 offset0:10 offset1:11
	v_mov_b32_e32 v5, v8
	v_pk_mul_f32 v[14:15], v[2:3], v[4:5]
	v_mov_b32_e32 v2, v41
	v_mov_b32_e32 v5, v9
	v_pk_mul_f32 v[8:9], v[2:3], v[4:5]
	v_add_f32_e32 v0, v14, v15
	v_add_f32_e32 v2, v8, v9
	v_mul_f32_e32 v13, v11, v2
	v_mov_b32_e32 v2, v42
	v_mul_f32_e32 v0, v11, v0
	s_waitcnt lgkmcnt(0)
	ds_read2st64_b32 v[8:9], v12 offset0:12 offset1:13
	v_mov_b32_e32 v5, v246
	v_pk_mul_f32 v[14:15], v[2:3], v[4:5]
	v_mov_b32_e32 v5, v247
	v_add_f32_e32 v2, v14, v15
	v_mul_f32_e32 v14, v11, v2
	v_mov_b32_e32 v2, v43
	v_pk_mul_f32 v[246:247], v[2:3], v[4:5]
	s_nop 0
	v_add_f32_e32 v2, v246, v247
	v_mul_f32_e32 v2, v11, v2
	v_cvt_pk_bf16_f32 v246, v0, v13
	v_cvt_pk_bf16_f32 v247, v14, v2
	global_store_dwordx2 v[6:7], v[246:247], off offset:32
	v_mov_b32_e32 v2, v44
	s_waitcnt lgkmcnt(0)
	ds_read2st64_b32 v[246:247], v12 offset0:14 offset1:15
	v_mov_b32_e32 v5, v8
	v_pk_mul_f32 v[14:15], v[2:3], v[4:5]
	v_mov_b32_e32 v2, v45
	v_mov_b32_e32 v5, v9
	v_pk_mul_f32 v[8:9], v[2:3], v[4:5]
	v_add_f32_e32 v0, v14, v15
	v_add_f32_e32 v2, v8, v9
	v_mul_f32_e32 v13, v11, v2
	v_mov_b32_e32 v2, v46
	v_mul_f32_e32 v0, v11, v0
	s_waitcnt lgkmcnt(0)
	ds_read2st64_b32 v[8:9], v12 offset0:16 offset1:17
	v_mov_b32_e32 v5, v246
	v_pk_mul_f32 v[14:15], v[2:3], v[4:5]
	v_mov_b32_e32 v5, v247
	v_add_f32_e32 v2, v14, v15
	v_mul_f32_e32 v14, v11, v2
	v_mov_b32_e32 v2, v47
	v_pk_mul_f32 v[246:247], v[2:3], v[4:5]
	s_nop 0
	v_add_f32_e32 v2, v246, v247
	v_mul_f32_e32 v2, v11, v2
	v_cvt_pk_bf16_f32 v246, v0, v13
	v_cvt_pk_bf16_f32 v247, v14, v2
	global_store_dwordx2 v[6:7], v[246:247], off offset:48
	v_mov_b32_e32 v2, v16
	s_waitcnt lgkmcnt(0)
	ds_read2st64_b32 v[246:247], v12 offset0:18 offset1:19
	v_mov_b32_e32 v5, v8
	v_pk_mul_f32 v[14:15], v[2:3], v[4:5]
	v_mov_b32_e32 v2, v17
	v_mov_b32_e32 v5, v9
	v_pk_mul_f32 v[8:9], v[2:3], v[4:5]
	v_add_f32_e32 v0, v14, v15
	v_add_f32_e32 v2, v8, v9
	v_mul_f32_e32 v13, v11, v2
	v_mov_b32_e32 v2, v18
	v_mul_f32_e32 v0, v11, v0
	s_waitcnt lgkmcnt(0)
	ds_read2st64_b32 v[8:9], v12 offset0:20 offset1:21
	v_mov_b32_e32 v5, v246
	v_pk_mul_f32 v[14:15], v[2:3], v[4:5]
	v_mov_b32_e32 v5, v247
	v_add_f32_e32 v2, v14, v15
	v_mul_f32_e32 v14, v11, v2
	v_mov_b32_e32 v2, v19
	v_pk_mul_f32 v[246:247], v[2:3], v[4:5]
	s_nop 0
	v_add_f32_e32 v2, v246, v247
	v_mul_f32_e32 v2, v11, v2
	v_cvt_pk_bf16_f32 v246, v0, v13
	v_cvt_pk_bf16_f32 v247, v14, v2
	global_store_dwordx2 v[6:7], v[246:247], off offset:64
	v_mov_b32_e32 v2, v20
	s_waitcnt lgkmcnt(0)
	ds_read2st64_b32 v[246:247], v12 offset0:22 offset1:23
	v_mov_b32_e32 v5, v8
	v_pk_mul_f32 v[14:15], v[2:3], v[4:5]
	v_mov_b32_e32 v2, v21
	v_mov_b32_e32 v5, v9
	v_pk_mul_f32 v[8:9], v[2:3], v[4:5]
	v_add_f32_e32 v0, v14, v15
	v_add_f32_e32 v2, v8, v9
	v_mul_f32_e32 v13, v11, v2
	v_mov_b32_e32 v2, v22
	v_mul_f32_e32 v0, v11, v0
	s_waitcnt lgkmcnt(0)
	ds_read2st64_b32 v[8:9], v12 offset0:24 offset1:25
	v_mov_b32_e32 v5, v246
	v_pk_mul_f32 v[14:15], v[2:3], v[4:5]
	v_mov_b32_e32 v5, v247
	v_add_f32_e32 v2, v14, v15
	v_mul_f32_e32 v14, v11, v2
	v_mov_b32_e32 v2, v23
	v_pk_mul_f32 v[246:247], v[2:3], v[4:5]
	s_nop 0
	v_add_f32_e32 v2, v246, v247
	v_mul_f32_e32 v2, v11, v2
	v_cvt_pk_bf16_f32 v246, v0, v13
	v_cvt_pk_bf16_f32 v247, v14, v2
	global_store_dwordx2 v[6:7], v[246:247], off offset:80
	v_mov_b32_e32 v2, v24
	s_waitcnt lgkmcnt(0)
	ds_read2st64_b32 v[246:247], v12 offset0:26 offset1:27
	v_mov_b32_e32 v5, v8
	v_pk_mul_f32 v[14:15], v[2:3], v[4:5]
	v_mov_b32_e32 v2, v25
	v_mov_b32_e32 v5, v9
	v_pk_mul_f32 v[8:9], v[2:3], v[4:5]
	v_add_f32_e32 v0, v14, v15
	v_add_f32_e32 v2, v8, v9
	v_mul_f32_e32 v13, v11, v2
	v_mov_b32_e32 v2, v26
	v_mul_f32_e32 v0, v11, v0
	s_waitcnt lgkmcnt(0)
	ds_read2st64_b32 v[8:9], v12 offset0:28 offset1:29
	v_mov_b32_e32 v5, v246
	v_pk_mul_f32 v[14:15], v[2:3], v[4:5]
	v_mov_b32_e32 v5, v247
	v_add_f32_e32 v2, v14, v15
	v_mul_f32_e32 v14, v11, v2
	v_mov_b32_e32 v2, v27
	v_pk_mul_f32 v[246:247], v[2:3], v[4:5]
	s_nop 0
	v_add_f32_e32 v2, v246, v247
	v_mul_f32_e32 v2, v11, v2
	v_cvt_pk_bf16_f32 v246, v0, v13
	v_cvt_pk_bf16_f32 v247, v14, v2
	global_store_dwordx2 v[6:7], v[246:247], off offset:96
	v_mov_b32_e32 v2, v28
	s_waitcnt lgkmcnt(0)
	ds_read2st64_b32 v[246:247], v12 offset0:30 offset1:31
	v_mov_b32_e32 v5, v8
	v_pk_mul_f32 v[14:15], v[2:3], v[4:5]
	v_mov_b32_e32 v2, v29
	v_mov_b32_e32 v5, v9
	v_pk_mul_f32 v[8:9], v[2:3], v[4:5]
	v_add_f32_e32 v0, v14, v15
	v_add_f32_e32 v2, v8, v9
	v_mul_f32_e32 v14, v11, v2
	v_mov_b32_e32 v2, v30
	v_mul_f32_e32 v0, v11, v0
	s_waitcnt lgkmcnt(0)
	v_mov_b32_e32 v5, v246
	v_pk_mul_f32 v[12:13], v[2:3], v[4:5]
	v_mov_b32_e32 v5, v247
	v_add_f32_e32 v2, v12, v13
	v_mul_f32_e32 v246, v11, v2
	v_mov_b32_e32 v2, v31
	v_pk_mul_f32 v[2:3], v[2:3], v[4:5]
	s_nop 0
	v_add_f32_e32 v2, v2, v3
	v_mul_f32_e32 v3, v11, v2
	v_cvt_pk_bf16_f32 v2, v0, v14
	v_cvt_pk_bf16_f32 v3, v246, v3
	global_store_dwordx2 v[6:7], v[2:3], off offset:112
	s_and_saveexec_b64 s[8:9], s[50:51]
	s_cbranch_execnz .LBB0_421
	s_branch .LBB0_422

; __device__ __forceinline__ float fast_exp2(float x) { return __builtin_amdgcn_exp2f(x); }
; template <int DQ, int TYPE>
; __device__ __forceinline__ void attn_item(PP p, int layer, int b, int h, int qt, char* lds, const int tid_, unsigned* next_ctr, volatile XLAS unsigned* slot) {
;     ...
;         const float* mp = mrg + (size_t)((qg * 2 + (kh ^ 1)) * 34) * 64 + lane;
;         const float m1 = mp[32 * 64], l1 = mp[33 * 64];
;         const float mt = fmaxf(m_run, m1);
;         const float a0 = fast_exp2(m_run - mt), a1 = fast_exp2(m1 - mt);
;         const float inv = 1.0f / (l_run * a0 + l1 * a1);
;         bf16_t* orow = Op + (size_t)qpos * D;
;     ...
;         if (kh == 0) A_MERGE(0); else A_MERGE(2);
.LBB0_683:
	ds_read2st64_b32 v[36:37], v76 offset1:1
	v_mov_b32_e32 v66, v18
	v_lshl_add_u64 v[34:35], v[70:71], 0, v[0:1]
	s_waitcnt lgkmcnt(0)
	v_mov_b32_e32 v69, v36
	v_pk_mul_f32 v[38:39], v[66:67], v[68:69]
	v_mov_b32_e32 v66, v19
	v_mov_b32_e32 v69, v37
	v_pk_mul_f32 v[18:19], v[66:67], v[68:69]
	v_add_f32_e32 v0, v38, v39
	v_add_f32_e32 v18, v18, v19
	v_mul_f32_e32 v38, v75, v18
	ds_read2st64_b32 v[18:19], v76 offset0:2 offset1:3
	v_mov_b32_e32 v66, v20
	v_mul_f32_e32 v0, v75, v0
	s_waitcnt lgkmcnt(0)
	ds_read2st64_b32 v[246:247], v76 offset0:4 offset1:5
	v_mov_b32_e32 v69, v18
	v_pk_mul_f32 v[36:37], v[66:67], v[68:69]
	v_mov_b32_e32 v66, v21
	v_add_f32_e32 v18, v36, v37
	v_mov_b32_e32 v69, v19
	v_mul_f32_e32 v20, v75, v18
	v_pk_mul_f32 v[18:19], v[66:67], v[68:69]
	v_mov_b32_e32 v66, v22
	v_add_f32_e32 v18, v18, v19
	v_mul_f32_e32 v19, v75, v18
	v_cvt_pk_bf16_f32 v18, v0, v38
	v_cvt_pk_bf16_f32 v19, v20, v19
	global_store_dwordx2 v[34:35], v[18:19], off
	s_waitcnt lgkmcnt(0)
	ds_read2st64_b32 v[18:19], v76 offset0:6 offset1:7
	v_mov_b32_e32 v69, v246
	v_pk_mul_f32 v[20:21], v[66:67], v[68:69]
	v_mov_b32_e32 v66, v23
	v_mov_b32_e32 v69, v247
	v_pk_mul_f32 v[246:247], v[66:67], v[68:69]
	v_mov_b32_e32 v66, v24
	v_add_f32_e32 v246, v246, v247
	v_mul_f32_e32 v22, v75, v246
	v_add_f32_e32 v0, v20, v21
	v_mul_f32_e32 v0, v75, v0
	s_waitcnt lgkmcnt(0)
	ds_read2st64_b32 v[246:247], v76 offset0:8 offset1:9
	v_mov_b32_e32 v69, v18
	v_pk_mul_f32 v[20:21], v[66:67], v[68:69]
	v_mov_b32_e32 v66, v25
	v_add_f32_e32 v18, v20, v21
	v_mov_b32_e32 v69, v19
	v_mul_f32_e32 v20, v75, v18
	v_pk_mul_f32 v[18:19], v[66:67], v[68:69]
	v_mov_b32_e32 v66, v26
	v_add_f32_e32 v18, v18, v19
	v_mul_f32_e32 v19, v75, v18
	v_cvt_pk_bf16_f32 v18, v0, v22
	v_cvt_pk_bf16_f32 v19, v20, v19
	global_store_dwordx2 v[34:35], v[18:19], off offset:16
	s_waitcnt lgkmcnt(0)
	ds_read2st64_b32 v[18:19], v76 offset0:10 offset1:11
	v_mov_b32_e32 v69, v246
	v_pk_mul_f32 v[20:21], v[66:67], v[68:69]
	v_mov_b32_e32 v66, v27
	v_mov_b32_e32 v69, v247
	v_pk_mul_f32 v[246:247], v[66:67], v[68:69]
	v_mov_b32_e32 v66, v28
	v_add_f32_e32 v246, v246, v247
	v_mul_f32_e32 v22, v75, v246
	v_add_f32_e32 v0, v20, v21
	v_mul_f32_e32 v0, v75, v0
	s_waitcnt lgkmcnt(0)
	ds_read2st64_b32 v[246:247], v76 offset0:12 offset1:13
	v_mov_b32_e32 v69, v18
	v_pk_mul_f32 v[20:21], v[66:67], v[68:69]
	v_mov_b32_e32 v66, v29
	v_add_f32_e32 v18, v20, v21
	v_mov_b32_e32 v69, v19
	v_mul_f32_e32 v20, v75, v18
	v_pk_mul_f32 v[18:19], v[66:67], v[68:69]
	v_mov_b32_e32 v66, v30
	v_add_f32_e32 v18, v18, v19
	v_mul_f32_e32 v19, v75, v18
	v_cvt_pk_bf16_f32 v18, v0, v22
	v_cvt_pk_bf16_f32 v19, v20, v19
	global_store_dwordx2 v[34:35], v[18:19], off offset:32
	s_waitcnt lgkmcnt(0)
	ds_read2st64_b32 v[18:19], v76 offset0:14 offset1:15
	v_mov_b32_e32 v69, v246
	v_pk_mul_f32 v[20:21], v[66:67], v[68:69]
	v_mov_b32_e32 v66, v31
	v_mov_b32_e32 v69, v247
	v_pk_mul_f32 v[246:247], v[66:67], v[68:69]
	v_mov_b32_e32 v66, v32
	v_add_f32_e32 v246, v246, v247
	v_mul_f32_e32 v22, v75, v246
	v_add_f32_e32 v0, v20, v21
	v_mul_f32_e32 v0, v75, v0
	s_waitcnt lgkmcnt(0)
	ds_read2st64_b32 v[246:247], v76 offset0:16 offset1:17
	v_mov_b32_e32 v69, v18
	v_pk_mul_f32 v[20:21], v[66:67], v[68:69]
	v_mov_b32_e32 v66, v33
	v_add_f32_e32 v18, v20, v21
	v_mov_b32_e32 v69, v19
	v_mul_f32_e32 v20, v75, v18
	v_pk_mul_f32 v[18:19], v[66:67], v[68:69]
	v_mov_b32_e32 v66, v2
	v_add_f32_e32 v18, v18, v19
	v_mul_f32_e32 v19, v75, v18
	v_cvt_pk_bf16_f32 v18, v0, v22
	v_cvt_pk_bf16_f32 v19, v20, v19
	global_store_dwordx2 v[34:35], v[18:19], off offset:48
	s_waitcnt lgkmcnt(0)
	v_mov_b32_e32 v69, v246
	v_pk_mul_f32 v[20:21], v[66:67], v[68:69]
	v_mov_b32_e32 v66, v3
	v_mov_b32_e32 v69, v247
	v_pk_mul_f32 v[2:3], v[66:67], v[68:69]
	v_add_f32_e32 v0, v20, v21
	v_add_f32_e32 v2, v2, v3
	v_mul_f32_e32 v20, v75, v2
	ds_read2st64_b32 v[2:3], v76 offset0:18 offset1:19
	v_mov_b32_e32 v66, v4
	v_mul_f32_e32 v0, v75, v0
	s_waitcnt lgkmcnt(0)
	ds_read2st64_b32 v[246:247], v76 offset0:20 offset1:21
	v_mov_b32_e32 v69, v2
	v_pk_mul_f32 v[18:19], v[66:67], v[68:69]
	v_mov_b32_e32 v66, v5
	v_add_f32_e32 v2, v18, v19
	v_mov_b32_e32 v69, v3
	v_mul_f32_e32 v4, v75, v2
	v_pk_mul_f32 v[2:3], v[66:67], v[68:69]
	v_mov_b32_e32 v66, v6
	v_add_f32_e32 v2, v2, v3
	v_mul_f32_e32 v3, v75, v2
	v_cvt_pk_bf16_f32 v2, v0, v20
	v_cvt_pk_bf16_f32 v3, v4, v3
	global_store_dwordx2 v[34:35], v[2:3], off offset:64
	s_waitcnt lgkmcnt(0)
	ds_read2st64_b32 v[2:3], v76 offset0:22 offset1:23
	v_mov_b32_e32 v69, v246
	v_pk_mul_f32 v[4:5], v[66:67], v[68:69]
	v_mov_b32_e32 v66, v7
	v_mov_b32_e32 v69, v247
	v_pk_mul_f32 v[246:247], v[66:67], v[68:69]
	v_mov_b32_e32 v66, v8
	v_add_f32_e32 v246, v246, v247
	v_mul_f32_e32 v6, v75, v246
	v_add_f32_e32 v0, v4, v5
	v_mul_f32_e32 v0, v75, v0
	s_waitcnt lgkmcnt(0)
	ds_read2st64_b32 v[246:247], v76 offset0:24 offset1:25
	v_mov_b32_e32 v69, v2
	v_pk_mul_f32 v[4:5], v[66:67], v[68:69]
	v_mov_b32_e32 v66, v9
	v_add_f32_e32 v2, v4, v5
	v_mov_b32_e32 v69, v3
	v_mul_f32_e32 v4, v75, v2
	v_pk_mul_f32 v[2:3], v[66:67], v[68:69]
	v_mov_b32_e32 v66, v10
	v_add_f32_e32 v2, v2, v3
	v_mul_f32_e32 v3, v75, v2
	v_cvt_pk_bf16_f32 v2, v0, v6
	v_cvt_pk_bf16_f32 v3, v4, v3
	global_store_dwordx2 v[34:35], v[2:3], off offset:80
	s_waitcnt lgkmcnt(0)
	ds_read2st64_b32 v[2:3], v76 offset0:26 offset1:27
	v_mov_b32_e32 v69, v246
	v_pk_mul_f32 v[4:5], v[66:67], v[68:69]
	v_mov_b32_e32 v66, v11
	v_mov_b32_e32 v69, v247
	v_pk_mul_f32 v[246:247], v[66:67], v[68:69]
	v_mov_b32_e32 v66, v12
	v_add_f32_e32 v246, v246, v247
	v_mul_f32_e32 v6, v75, v246
	v_add_f32_e32 v0, v4, v5
	v_mul_f32_e32 v0, v75, v0
	s_waitcnt lgkmcnt(0)
	ds_read2st64_b32 v[246:247], v76 offset0:28 offset1:29
	v_mov_b32_e32 v69, v2
	v_pk_mul_f32 v[4:5], v[66:67], v[68:69]
	v_mov_b32_e32 v66, v13
	v_add_f32_e32 v2, v4, v5
	v_mov_b32_e32 v69, v3
	v_mul_f32_e32 v4, v75, v2
	v_pk_mul_f32 v[2:3], v[66:67], v[68:69]
	v_mov_b32_e32 v66, v14
	v_add_f32_e32 v2, v2, v3
	v_mul_f32_e32 v3, v75, v2
	v_cvt_pk_bf16_f32 v2, v0, v6
	v_cvt_pk_bf16_f32 v3, v4, v3
	global_store_dwordx2 v[34:35], v[2:3], off offset:96
	s_waitcnt lgkmcnt(0)
	ds_read2st64_b32 v[2:3], v76 offset0:30 offset1:31
	v_mov_b32_e32 v69, v246
	v_pk_mul_f32 v[4:5], v[66:67], v[68:69]
	v_mov_b32_e32 v66, v15
	v_mov_b32_e32 v69, v247
	v_pk_mul_f32 v[246:247], v[66:67], v[68:69]
	v_mov_b32_e32 v66, v16
	v_add_f32_e32 v246, v246, v247
	v_mul_f32_e32 v6, v75, v246
	v_add_f32_e32 v0, v4, v5
	v_mul_f32_e32 v0, v75, v0
	s_waitcnt lgkmcnt(0)
	v_mov_b32_e32 v69, v2
	v_pk_mul_f32 v[4:5], v[66:67], v[68:69]
	v_mov_b32_e32 v66, v17
	v_add_f32_e32 v2, v4, v5
	v_mov_b32_e32 v69, v3
	v_mul_f32_e32 v4, v75, v2
	v_pk_mul_f32 v[2:3], v[66:67], v[68:69]
	s_nop 0
	v_add_f32_e32 v2, v2, v3
	v_mul_f32_e32 v3, v75, v2
	v_cvt_pk_bf16_f32 v2, v0, v6
	v_cvt_pk_bf16_f32 v3, v4, v3
	global_store_dwordx2 v[34:35], v[2:3], off offset:112
	s_and_saveexec_b64 s[8:9], s[50:51]
	s_cbranch_execnz .LBB0_656
	s_branch .LBB0_657

; __device__ __forceinline__ float fast_exp2(float x) { return __builtin_amdgcn_exp2f(x); }
; template <int DQ, int TYPE>
; __device__ __forceinline__ void attn_item(PP p, int layer, int b, int h, int qt, char* lds, const int tid_, unsigned* next_ctr, volatile XLAS unsigned* slot) {
;     ...
;         const float* mp = mrg + (size_t)((qg * 2 + (kh ^ 1)) * 34) * 64 + lane;
;         const float m1 = mp[32 * 64], l1 = mp[33 * 64];
;         const float mt = fmaxf(m_run, m1);
;         const float a0 = fast_exp2(m_run - mt), a1 = fast_exp2(m1 - mt);
;         const float inv = 1.0f / (l_run * a0 + l1 * a1);
;         bf16_t* orow = Op + (size_t)qpos * D;
;     ...
;         if (kh == 0) A_MERGE(0); else A_MERGE(2);
.LBB0_685:
	ds_read2st64_b32 v[36:37], v76 offset1:1
	v_mov_b32_e32 v66, v18
	v_lshl_add_u64 v[34:35], v[70:71], 0, v[0:1]
	s_waitcnt lgkmcnt(0)
	v_mov_b32_e32 v69, v36
	v_pk_mul_f32 v[38:39], v[66:67], v[68:69]
	v_mov_b32_e32 v66, v19
	v_mov_b32_e32 v69, v37
	v_pk_mul_f32 v[18:19], v[66:67], v[68:69]
	v_add_f32_e32 v0, v38, v39
	v_add_f32_e32 v18, v18, v19
	v_mul_f32_e32 v38, v75, v18
	ds_read2st64_b32 v[18:19], v76 offset0:2 offset1:3
	v_mov_b32_e32 v66, v20
	v_mul_f32_e32 v0, v75, v0
	s_waitcnt lgkmcnt(0)
	ds_read2st64_b32 v[246:247], v76 offset0:4 offset1:5
	v_mov_b32_e32 v69, v18
	v_pk_mul_f32 v[36:37], v[66:67], v[68:69]
	v_mov_b32_e32 v66, v21
	v_add_f32_e32 v18, v36, v37
	v_mov_b32_e32 v69, v19
	v_mul_f32_e32 v20, v75, v18
	v_pk_mul_f32 v[18:19], v[66:67], v[68:69]
	v_mov_b32_e32 v66, v22
	v_add_f32_e32 v18, v18, v19
	v_mul_f32_e32 v19, v75, v18
	v_cvt_pk_bf16_f32 v18, v0, v38
	v_cvt_pk_bf16_f32 v19, v20, v19
	global_store_dwordx2 v[34:35], v[18:19], off
	s_waitcnt lgkmcnt(0)
	ds_read2st64_b32 v[18:19], v76 offset0:6 offset1:7
	v_mov_b32_e32 v69, v246
	v_pk_mul_f32 v[20:21], v[66:67], v[68:69]
	v_mov_b32_e32 v66, v23
	v_mov_b32_e32 v69, v247
	v_pk_mul_f32 v[246:247], v[66:67], v[68:69]
	v_mov_b32_e32 v66, v24
	v_add_f32_e32 v246, v246, v247
	v_mul_f32_e32 v22, v75, v246
	v_add_f32_e32 v0, v20, v21
	v_mul_f32_e32 v0, v75, v0
	s_waitcnt lgkmcnt(0)
	ds_read2st64_b32 v[246:247], v76 offset0:8 offset1:9
	v_mov_b32_e32 v69, v18
	v_pk_mul_f32 v[20:21], v[66:67], v[68:69]
	v_mov_b32_e32 v66, v25
	v_add_f32_e32 v18, v20, v21
	v_mov_b32_e32 v69, v19
	v_mul_f32_e32 v20, v75, v18
	v_pk_mul_f32 v[18:19], v[66:67], v[68:69]
	v_mov_b32_e32 v66, v26
	v_add_f32_e32 v18, v18, v19
	v_mul_f32_e32 v19, v75, v18
	v_cvt_pk_bf16_f32 v18, v0, v22
	v_cvt_pk_bf16_f32 v19, v20, v19
	global_store_dwordx2 v[34:35], v[18:19], off offset:16
	s_waitcnt lgkmcnt(0)
	ds_read2st64_b32 v[18:19], v76 offset0:10 offset1:11
	v_mov_b32_e32 v69, v246
	v_pk_mul_f32 v[20:21], v[66:67], v[68:69]
	v_mov_b32_e32 v66, v27
	v_mov_b32_e32 v69, v247
	v_pk_mul_f32 v[246:247], v[66:67], v[68:69]
	v_mov_b32_e32 v66, v28
	v_add_f32_e32 v246, v246, v247
	v_mul_f32_e32 v22, v75, v246
	v_add_f32_e32 v0, v20, v21
	v_mul_f32_e32 v0, v75, v0
	s_waitcnt lgkmcnt(0)
	ds_read2st64_b32 v[246:247], v76 offset0:12 offset1:13
	v_mov_b32_e32 v69, v18
	v_pk_mul_f32 v[20:21], v[66:67], v[68:69]
	v_mov_b32_e32 v66, v29
	v_add_f32_e32 v18, v20, v21
	v_mov_b32_e32 v69, v19
	v_mul_f32_e32 v20, v75, v18
	v_pk_mul_f32 v[18:19], v[66:67], v[68:69]
	v_mov_b32_e32 v66, v30
	v_add_f32_e32 v18, v18, v19
	v_mul_f32_e32 v19, v75, v18
	v_cvt_pk_bf16_f32 v18, v0, v22
	v_cvt_pk_bf16_f32 v19, v20, v19
	global_store_dwordx2 v[34:35], v[18:19], off offset:32
	s_waitcnt lgkmcnt(0)
	ds_read2st64_b32 v[18:19], v76 offset0:14 offset1:15
	v_mov_b32_e32 v69, v246
	v_pk_mul_f32 v[20:21], v[66:67], v[68:69]
	v_mov_b32_e32 v66, v31
	v_mov_b32_e32 v69, v247
	v_pk_mul_f32 v[246:247], v[66:67], v[68:69]
	v_mov_b32_e32 v66, v32
	v_add_f32_e32 v246, v246, v247
	v_mul_f32_e32 v22, v75, v246
	v_add_f32_e32 v0, v20, v21
	v_mul_f32_e32 v0, v75, v0
	s_waitcnt lgkmcnt(0)
	ds_read2st64_b32 v[246:247], v76 offset0:16 offset1:17
	v_mov_b32_e32 v69, v18
	v_pk_mul_f32 v[20:21], v[66:67], v[68:69]
	v_mov_b32_e32 v66, v33
	v_add_f32_e32 v18, v20, v21
	v_mov_b32_e32 v69, v19
	v_mul_f32_e32 v20, v75, v18
	v_pk_mul_f32 v[18:19], v[66:67], v[68:69]
	v_mov_b32_e32 v66, v2
	v_add_f32_e32 v18, v18, v19
	v_mul_f32_e32 v19, v75, v18
	v_cvt_pk_bf16_f32 v18, v0, v22
	v_cvt_pk_bf16_f32 v19, v20, v19
	global_store_dwordx2 v[34:35], v[18:19], off offset:48
	s_waitcnt lgkmcnt(0)
	v_mov_b32_e32 v69, v246
	v_pk_mul_f32 v[20:21], v[66:67], v[68:69]
	v_mov_b32_e32 v66, v3
	v_mov_b32_e32 v69, v247
	v_pk_mul_f32 v[2:3], v[66:67], v[68:69]
	v_add_f32_e32 v0, v20, v21
	v_add_f32_e32 v2, v2, v3
	v_mul_f32_e32 v20, v75, v2
	ds_read2st64_b32 v[2:3], v76 offset0:18 offset1:19
	v_mov_b32_e32 v66, v4
	v_mul_f32_e32 v0, v75, v0
	s_waitcnt lgkmcnt(0)
	ds_read2st64_b32 v[246:247], v76 offset0:20 offset1:21
	v_mov_b32_e32 v69, v2
	v_pk_mul_f32 v[18:19], v[66:67], v[68:69]
	v_mov_b32_e32 v66, v5
	v_add_f32_e32 v2, v18, v19
	v_mov_b32_e32 v69, v3
	v_mul_f32_e32 v4, v75, v2
	v_pk_mul_f32 v[2:3], v[66:67], v[68:69]
	v_mov_b32_e32 v66, v6
	v_add_f32_e32 v2, v2, v3
	v_mul_f32_e32 v3, v75, v2
	v_cvt_pk_bf16_f32 v2, v0, v20
	v_cvt_pk_bf16_f32 v3, v4, v3
	global_store_dwordx2 v[34:35], v[2:3], off offset:64
	s_waitcnt lgkmcnt(0)
	ds_read2st64_b32 v[2:3], v76 offset0:22 offset1:23
	v_mov_b32_e32 v69, v246
	v_pk_mul_f32 v[4:5], v[66:67], v[68:69]
	v_mov_b32_e32 v66, v7
	v_mov_b32_e32 v69, v247
	v_pk_mul_f32 v[246:247], v[66:67], v[68:69]
	v_mov_b32_e32 v66, v8
	v_add_f32_e32 v246, v246, v247
	v_mul_f32_e32 v6, v75, v246
	v_add_f32_e32 v0, v4, v5
	v_mul_f32_e32 v0, v75, v0
	s_waitcnt lgkmcnt(0)
	ds_read2st64_b32 v[246:247], v76 offset0:24 offset1:25
	v_mov_b32_e32 v69, v2
	v_pk_mul_f32 v[4:5], v[66:67], v[68:69]
	v_mov_b32_e32 v66, v9
	v_add_f32_e32 v2, v4, v5
	v_mov_b32_e32 v69, v3
	v_mul_f32_e32 v4, v75, v2
	v_pk_mul_f32 v[2:3], v[66:67], v[68:69]
	v_mov_b32_e32 v66, v10
	v_add_f32_e32 v2, v2, v3
	v_mul_f32_e32 v3, v75, v2
	v_cvt_pk_bf16_f32 v2, v0, v6
	v_cvt_pk_bf16_f32 v3, v4, v3
	global_store_dwordx2 v[34:35], v[2:3], off offset:80
	s_waitcnt lgkmcnt(0)
	ds_read2st64_b32 v[2:3], v76 offset0:26 offset1:27
	v_mov_b32_e32 v69, v246
	v_pk_mul_f32 v[4:5], v[66:67], v[68:69]
	v_mov_b32_e32 v66, v11
	v_mov_b32_e32 v69, v247
	v_pk_mul_f32 v[246:247], v[66:67], v[68:69]
	v_mov_b32_e32 v66, v12
	v_add_f32_e32 v246, v246, v247
	v_mul_f32_e32 v6, v75, v246
	v_add_f32_e32 v0, v4, v5
	v_mul_f32_e32 v0, v75, v0
	s_waitcnt lgkmcnt(0)
	ds_read2st64_b32 v[246:247], v76 offset0:28 offset1:29
	v_mov_b32_e32 v69, v2
	v_pk_mul_f32 v[4:5], v[66:67], v[68:69]
	v_mov_b32_e32 v66, v13
	v_add_f32_e32 v2, v4, v5
	v_mov_b32_e32 v69, v3
	v_mul_f32_e32 v4, v75, v2
	v_pk_mul_f32 v[2:3], v[66:67], v[68:69]
	v_mov_b32_e32 v66, v14
	v_add_f32_e32 v2, v2, v3
	v_mul_f32_e32 v3, v75, v2
	v_cvt_pk_bf16_f32 v2, v0, v6
	v_cvt_pk_bf16_f32 v3, v4, v3
	global_store_dwordx2 v[34:35], v[2:3], off offset:96
	s_waitcnt lgkmcnt(0)
	ds_read2st64_b32 v[2:3], v76 offset0:30 offset1:31
	v_mov_b32_e32 v69, v246
	v_pk_mul_f32 v[4:5], v[66:67], v[68:69]
	v_mov_b32_e32 v66, v15
	v_mov_b32_e32 v69, v247
	v_pk_mul_f32 v[246:247], v[66:67], v[68:69]
	v_mov_b32_e32 v66, v16
	v_add_f32_e32 v246, v246, v247
	v_mul_f32_e32 v6, v75, v246
	v_add_f32_e32 v0, v4, v5
	v_mul_f32_e32 v0, v75, v0
	s_waitcnt lgkmcnt(0)
	v_mov_b32_e32 v69, v2
	v_pk_mul_f32 v[4:5], v[66:67], v[68:69]
	v_mov_b32_e32 v66, v17
	v_add_f32_e32 v2, v4, v5
	v_mov_b32_e32 v69, v3
	v_mul_f32_e32 v4, v75, v2
	v_pk_mul_f32 v[2:3], v[66:67], v[68:69]
	s_nop 0
	v_add_f32_e32 v2, v2, v3
	v_mul_f32_e32 v3, v75, v2
	v_cvt_pk_bf16_f32 v2, v0, v6
	v_cvt_pk_bf16_f32 v3, v4, v3
	global_store_dwordx2 v[34:35], v[2:3], off offset:112
	s_and_saveexec_b64 s[8:9], s[50:51]
	s_cbranch_execz .LBB0_384
